# v041 plus the duplicate post-barrier waits removed in the P1 K-loop and the priority flip pairs between the MFMA half-blocks removed in P3-P6
# baseline (speedup 1.0000x reference)
; #define PG8_STAGE(bufoff, gbase, voff) do { _Pragma("unroll") for (int _i = 0; _i < 2; ++_i) { unsigned vo_ = (voff)[_i]; if constexpr (FP8) asm volatile("" : "+v"(vo_)); \
;         __builtin_amdgcn_global_load_lds((const unsigned*)((const char*)(gbase) + vo_), (PG8_LAS unsigned*)(lds + (bufoff) + ldsw + _i * 8192), 16, 0, 0); } } while (0)
; #define PG8_LDA(dst, b, h) do { _Pragma("unroll") for (int m = 0; m < 4; ++m) _Pragma("unroll") for (int k = 0; k < 2; ++k) dst[m][k] = *(const PG8_LAS bf16x8*)(lds + PG8_SA(b, h) + aoff + m * 2048 + k * 1024); } while (0)
; #define PG8_LDB(dst, b, h) do { _Pragma("unroll") for (int n = 0; n < 2; ++n) _Pragma("unroll") for (int k = 0; k < 2; ++k) dst[n][k] = *(const PG8_LAS bf16x8*)(lds + PG8_SB(b, h) + boff + n * 2048 + k * 1024); } while (0)
; #define PG8_WAIT_V(n) asm volatile("s_waitcnt vmcnt(" #n ")" ::: "memory")
; #define PG8_WAIT_L(n) asm volatile("s_waitcnt lgkmcnt(" #n ")" ::: "memory")
; #define PG8_BAR __builtin_amdgcn_s_barrier()
; #define PG8_SCHED __builtin_amdgcn_sched_barrier(0)
; template <class Epi, class Sched, bool ALIGN_EPI = false, bool SP2 = false, bool FP8 = false>
; __device__ __forceinline__ void gemm_phase(PG8_LAS unsigned char* lds, const Gemm g, const Sched& S, const Epi& E) {
;     ...
;             PG8_LDB(B0, 0, 0); PG8_LDB(B1, 0, 1); PG8_SCHED; PG8_LDA(At, 0, 0); PG8_STAGE(PG8_SA(1, 1), a1 + hstep, voffA);
;             PG8_WAIT_V(8); PG8_WAIT_L(0); PG8_BAR; PG8_MMA(0, 0, At, B0); PG8_MMA(0, 1, At, B1); PG8_BAR; PG8_SCHED;
;             PG8_LDA(At, 0, 1); PG8_STAGE(PG8_SB(0, 0), b2, voffB); PG8_STAGE(PG8_SB(0, 1), b2 + hstep, voffB); PG8_STAGE(PG8_SA(0, 0), a2, voffA);
;             PG8_WAIT_V(8); PG8_WAIT_L(0); PG8_BAR; PG8_MMA(1, 0, At, B0); PG8_MMA(1, 1, At, B1); PG8_BAR; PG8_SCHED;
.LBB0_305:
	s_add_u32 s52, s10, 0xfffe8080
	s_addc_u32 s53, s11, -1
	s_and_b64 s[0:1], s[62:63], exec
	s_cselect_b32 s65, s5, s53
	s_cselect_b32 s64, s4, s52
	s_add_i32 s52, 0, 0x10000
	v_add_u32_e32 v128, s52, v152
	ds_read_b128 v[134:137], v128
	ds_read_b128 v[138:141], v128 offset:1024
	ds_read_b128 v[156:159], v128 offset:2048
	ds_read_b128 v[160:163], v128 offset:3072
	v_add_u32_e32 v128, s84, v152
	ds_read_b128 v[164:167], v128
	ds_read_b128 v[168:171], v128 offset:1024
	ds_read_b128 v[178:181], v128 offset:2048
	ds_read_b128 v[182:185], v128 offset:3072
	s_and_b64 s[0:1], s[62:63], exec
	s_cselect_b32 s63, s61, s90
	s_cselect_b32 s62, s60, s89
	v_mov_b32_e32 v128, v146
	ds_read_b128 v[186:189], v153
	ds_read_b128 v[190:193], v153 offset:1024
	ds_read_b128 v[198:201], v153 offset:2048
	ds_read_b128 v[202:205], v153 offset:3072
	ds_read_b128 v[206:209], v153 offset:4096
	ds_read_b128 v[210:213], v153 offset:5120
	ds_read_b128 v[214:217], v153 offset:6144
	ds_read_b128 v[218:221], v153 offset:7168
	s_add_i32 m0, s68, 0xc000
	s_nop 0
	global_load_lds_dwordx4 v128, s[10:11]
	v_mov_b32_e32 v128, v148
	s_add_i32 m0, s68, 0xe000
	s_nop 0
	global_load_lds_dwordx4 v128, s[10:11]
	s_waitcnt vmcnt(8)
	s_waitcnt lgkmcnt(0)
	s_barrier
	s_setprio 1
	v_mfma_scale_f32_16x16x128_f8f6f4 v[112:115], v[134:141], v[186:193], v[112:115], v154, v154 op_sel_hi:[0,0,0]
	v_mfma_scale_f32_16x16x128_f8f6f4 v[116:119], v[156:163], v[186:193], v[116:119], v154, v154 op_sel_hi:[0,0,0]
	v_mfma_scale_f32_16x16x128_f8f6f4 v[96:99], v[134:141], v[198:205], v[96:99], v154, v154 op_sel_hi:[0,0,0]
	v_mfma_scale_f32_16x16x128_f8f6f4 v[100:103], v[156:163], v[198:205], v[100:103], v154, v154 op_sel_hi:[0,0,0]
	v_mfma_scale_f32_16x16x128_f8f6f4 v[142:145], v[134:141], v[206:213], v[80:83], v154, v154 op_sel_hi:[0,0,0]
	v_mfma_scale_f32_16x16x128_f8f6f4 v[172:175], v[156:163], v[206:213], v[84:87], v154, v154 op_sel_hi:[0,0,0]
	v_mfma_scale_f32_16x16x128_f8f6f4 v[194:197], v[134:141], v[214:221], v[64:67], v154, v154 op_sel_hi:[0,0,0]
	v_mfma_scale_f32_16x16x128_f8f6f4 v[222:225], v[156:163], v[214:221], v[68:71], v154, v154 op_sel_hi:[0,0,0]
	v_mfma_scale_f32_16x16x128_f8f6f4 v[120:123], v[164:171], v[186:193], v[120:123], v154, v154 op_sel_hi:[0,0,0]
	v_mfma_scale_f32_16x16x128_f8f6f4 v[124:127], v[178:185], v[186:193], v[124:127], v154, v154 op_sel_hi:[0,0,0]
	v_mfma_scale_f32_16x16x128_f8f6f4 v[104:107], v[164:171], v[198:205], v[104:107], v154, v154 op_sel_hi:[0,0,0]
	v_mfma_scale_f32_16x16x128_f8f6f4 v[108:111], v[178:185], v[198:205], v[108:111], v154, v154 op_sel_hi:[0,0,0]
	v_mfma_scale_f32_16x16x128_f8f6f4 v[186:189], v[164:171], v[206:213], v[88:91], v154, v154 op_sel_hi:[0,0,0]
	v_mfma_scale_f32_16x16x128_f8f6f4 v[190:193], v[178:185], v[206:213], v[92:95], v154, v154 op_sel_hi:[0,0,0]
	v_mfma_scale_f32_16x16x128_f8f6f4 v[198:201], v[164:171], v[214:221], v[72:75], v154, v154 op_sel_hi:[0,0,0]
	v_mfma_scale_f32_16x16x128_f8f6f4 v[202:205], v[178:185], v[214:221], v[76:79], v154, v154 op_sel_hi:[0,0,0]
	s_setprio 0
	s_barrier
	v_mov_b32_e32 v128, v147
	s_add_i32 s0, s52, s66
	ds_read_b128 v[64:67], v153 offset:16384
	ds_read_b128 v[68:71], v153 offset:17408
	ds_read_b128 v[72:75], v153 offset:18432
	ds_read_b128 v[76:79], v153 offset:19456
	ds_read_b128 v[80:83], v153 offset:20480
	ds_read_b128 v[84:87], v153 offset:21504
	ds_read_b128 v[88:91], v153 offset:22528
	ds_read_b128 v[92:95], v153 offset:23552
	s_mov_b32 m0, s0
	s_nop 0
	global_load_lds_dwordx4 v128, s[62:63]
	v_mov_b32_e32 v128, v149
	s_add_i32 m0, s0, 0x2000
	s_add_u32 s0, s62, 0x18000
	global_load_lds_dwordx4 v128, s[62:63]
	s_addc_u32 s1, s63, 0
	v_mov_b32_e32 v128, v147
	s_add_i32 s52, s84, s66
	s_mov_b32 m0, s52
	s_nop 0
	global_load_lds_dwordx4 v128, s[0:1]
	v_mov_b32_e32 v128, v149
	s_add_i32 m0, s52, 0x2000
	s_nop 0
	global_load_lds_dwordx4 v128, s[0:1]
	v_mov_b32_e32 v128, v146
	s_mov_b32 m0, s68
	s_nop 0
	global_load_lds_dwordx4 v128, s[64:65]
	v_mov_b32_e32 v128, v148
	s_mov_b32 m0, s69
	s_nop 0
	global_load_lds_dwordx4 v128, s[64:65]
	s_waitcnt vmcnt(8)
	s_waitcnt lgkmcnt(0)
	s_barrier
	s_setprio 1
	v_mfma_scale_f32_16x16x128_f8f6f4 v[48:51], v[134:141], v[64:71], v[48:51], v154, v154 op_sel_hi:[0,0,0]
	v_mfma_scale_f32_16x16x128_f8f6f4 v[52:55], v[156:163], v[64:71], v[52:55], v154, v154 op_sel_hi:[0,0,0]
	v_mfma_scale_f32_16x16x128_f8f6f4 v[206:209], v[134:141], v[72:79], v[32:35], v154, v154 op_sel_hi:[0,0,0]
	v_mfma_scale_f32_16x16x128_f8f6f4 v[210:213], v[156:163], v[72:79], v[36:39], v154, v154 op_sel_hi:[0,0,0]
	v_mfma_scale_f32_16x16x128_f8f6f4 v[214:217], v[134:141], v[80:87], v[16:19], v154, v154 op_sel_hi:[0,0,0]
	v_mfma_scale_f32_16x16x128_f8f6f4 v[218:221], v[156:163], v[80:87], v[20:23], v154, v154 op_sel_hi:[0,0,0]
	v_mfma_scale_f32_16x16x128_f8f6f4 v[226:229], v[134:141], v[88:95], v[4:7], v154, v154 op_sel_hi:[0,0,0]
	v_mfma_scale_f32_16x16x128_f8f6f4 v[230:233], v[156:163], v[88:95], v[8:11], v154, v154 op_sel_hi:[0,0,0]
	v_mfma_scale_f32_16x16x128_f8f6f4 v[56:59], v[164:171], v[64:71], v[56:59], v154, v154 op_sel_hi:[0,0,0]
	v_mfma_scale_f32_16x16x128_f8f6f4 v[60:63], v[178:185], v[64:71], v[60:63], v154, v154 op_sel_hi:[0,0,0]
	v_mfma_scale_f32_16x16x128_f8f6f4 v[234:237], v[164:171], v[72:79], v[40:43], v154, v154 op_sel_hi:[0,0,0]
	v_mfma_scale_f32_16x16x128_f8f6f4 v[238:241], v[178:185], v[72:79], v[44:47], v154, v154 op_sel_hi:[0,0,0]
	v_mfma_scale_f32_16x16x128_f8f6f4 v[242:245], v[164:171], v[80:87], v[24:27], v154, v154 op_sel_hi:[0,0,0]
	v_mfma_scale_f32_16x16x128_f8f6f4 v[246:249], v[178:185], v[80:87], v[28:31], v154, v154 op_sel_hi:[0,0,0]
	v_mfma_scale_f32_16x16x128_f8f6f4 v[250:253], v[164:171], v[88:95], v[12:15], v154, v154 op_sel_hi:[0,0,0]
	v_mfma_scale_f32_16x16x128_f8f6f4 v[130:133], v[178:185], v[88:95], v[0:3], v154, v154 op_sel_hi:[0,0,0]
	s_setprio 0
	s_barrier
; #define PG8_STAGE(bufoff, gbase, voff) do { _Pragma("unroll") for (int _i = 0; _i < 2; ++_i) { unsigned vo_ = (voff)[_i]; if constexpr (FP8) asm volatile("" : "+v"(vo_)); \
;         __builtin_amdgcn_global_load_lds((const unsigned*)((const char*)(gbase) + vo_), (PG8_LAS unsigned*)(lds + (bufoff) + ldsw + _i * 8192), 16, 0, 0); } } while (0)
; #define PG8_LDA(dst, b, h) do { _Pragma("unroll") for (int m = 0; m < 4; ++m) _Pragma("unroll") for (int k = 0; k < 2; ++k) dst[m][k] = *(const PG8_LAS bf16x8*)(lds + PG8_SA(b, h) + aoff + m * 2048 + k * 1024); } while (0)
; #define PG8_LDB(dst, b, h) do { _Pragma("unroll") for (int n = 0; n < 2; ++n) _Pragma("unroll") for (int k = 0; k < 2; ++k) dst[n][k] = *(const PG8_LAS bf16x8*)(lds + PG8_SB(b, h) + boff + n * 2048 + k * 1024); } while (0)
; #define PG8_WAIT_V(n) asm volatile("s_waitcnt vmcnt(" #n ")" ::: "memory")
; #define PG8_WAIT_L(n) asm volatile("s_waitcnt lgkmcnt(" #n ")" ::: "memory")
; #define PG8_BAR __builtin_amdgcn_s_barrier()
; #define PG8_SCHED __builtin_amdgcn_sched_barrier(0)
; template <class Epi, class Sched, bool ALIGN_EPI = false, bool SP2 = false, bool FP8 = false>
; __device__ __forceinline__ void gemm_phase(PG8_LAS unsigned char* lds, const Gemm g, const Sched& S, const Epi& E) {
;     ...
;             PG8_LDB(B0, 1, 0); PG8_LDB(B1, 1, 1); PG8_SCHED; PG8_LDA(At, 1, 0); PG8_STAGE(PG8_SA(0, 1), a2 + hstep, voffA);
;             PG8_WAIT_V(8); PG8_WAIT_L(0); PG8_BAR; PG8_MMA(0, 0, At, B0); PG8_MMA(0, 1, At, B1); PG8_BAR; PG8_SCHED;
;             PG8_LDA(At, 1, 1); PG8_STAGE(PG8_SB(1, 0), b3, voffB); PG8_STAGE(PG8_SB(1, 1), b3 + hstep, voffB); PG8_STAGE(PG8_SA(1, 0), a3, voffA);
;             PG8_WAIT_V(8); PG8_WAIT_L(0); PG8_BAR; PG8_MMA(1, 0, At, B0); PG8_MMA(1, 1, At, B1); PG8_BAR; PG8_SCHED;
	s_add_i32 s52, 0, 0x18000
	s_add_i32 s53, 0, 0x1c000
	s_nop 1
	v_add_u32_e32 v12, s52, v152
	v_add_u32_e32 v16, s53, v152
	ds_read_b128 v[0:3], v12
	ds_read_b128 v[4:7], v12 offset:1024
	ds_read_b128 v[8:11], v12 offset:2048
	ds_read_b128 v[12:15], v12 offset:3072
	ds_read_b128 v[134:137], v16
	ds_read_b128 v[138:141], v16 offset:1024
	ds_read_b128 v[156:159], v16 offset:2048
	ds_read_b128 v[160:163], v16 offset:3072
	s_add_u32 s0, s64, 0x18000
	v_mov_b32_e32 v64, v146
	s_mov_b32 m0, s70
	ds_read_b128 v[16:19], v153 offset:32768
	ds_read_b128 v[20:23], v153 offset:33792
	ds_read_b128 v[24:27], v153 offset:34816
	ds_read_b128 v[28:31], v153 offset:35840
	ds_read_b128 v[32:35], v153 offset:36864
	ds_read_b128 v[36:39], v153 offset:37888
	ds_read_b128 v[40:43], v153 offset:38912
	ds_read_b128 v[44:47], v153 offset:39936
	s_addc_u32 s1, s65, 0
	s_nop 0
	global_load_lds_dwordx4 v64, s[0:1]
	v_mov_b32_e32 v64, v148
	s_mov_b32 m0, s71
	s_nop 0
	global_load_lds_dwordx4 v64, s[0:1]
	s_waitcnt vmcnt(8)
	s_waitcnt lgkmcnt(0)
	s_barrier
	s_setprio 1
	v_mfma_scale_f32_16x16x128_f8f6f4 v[112:115], v[0:7], v[16:23], v[112:115], v154, v154 op_sel_hi:[0,0,0]
	v_mfma_scale_f32_16x16x128_f8f6f4 v[116:119], v[8:15], v[16:23], v[116:119], v154, v154 op_sel_hi:[0,0,0]
	v_mfma_scale_f32_16x16x128_f8f6f4 v[96:99], v[0:7], v[24:31], v[96:99], v154, v154 op_sel_hi:[0,0,0]
	v_mfma_scale_f32_16x16x128_f8f6f4 v[100:103], v[8:15], v[24:31], v[100:103], v154, v154 op_sel_hi:[0,0,0]
	v_mfma_scale_f32_16x16x128_f8f6f4 v[80:83], v[0:7], v[32:39], v[142:145], v154, v154 op_sel_hi:[0,0,0]
	v_mfma_scale_f32_16x16x128_f8f6f4 v[84:87], v[8:15], v[32:39], v[172:175], v154, v154 op_sel_hi:[0,0,0]
	v_mfma_scale_f32_16x16x128_f8f6f4 v[64:67], v[0:7], v[40:47], v[194:197], v154, v154 op_sel_hi:[0,0,0]
	v_mfma_scale_f32_16x16x128_f8f6f4 v[68:71], v[8:15], v[40:47], v[222:225], v154, v154 op_sel_hi:[0,0,0]
	v_mfma_scale_f32_16x16x128_f8f6f4 v[120:123], v[134:141], v[16:23], v[120:123], v154, v154 op_sel_hi:[0,0,0]
	v_mfma_scale_f32_16x16x128_f8f6f4 v[124:127], v[156:163], v[16:23], v[124:127], v154, v154 op_sel_hi:[0,0,0]
	v_mfma_scale_f32_16x16x128_f8f6f4 v[104:107], v[134:141], v[24:31], v[104:107], v154, v154 op_sel_hi:[0,0,0]
	v_mfma_scale_f32_16x16x128_f8f6f4 v[108:111], v[156:163], v[24:31], v[108:111], v154, v154 op_sel_hi:[0,0,0]
	v_mfma_scale_f32_16x16x128_f8f6f4 v[88:91], v[134:141], v[32:39], v[186:189], v154, v154 op_sel_hi:[0,0,0]
	v_mfma_scale_f32_16x16x128_f8f6f4 v[92:95], v[156:163], v[32:39], v[190:193], v154, v154 op_sel_hi:[0,0,0]
	v_mfma_scale_f32_16x16x128_f8f6f4 v[72:75], v[134:141], v[40:47], v[198:201], v154, v154 op_sel_hi:[0,0,0]
	v_mfma_scale_f32_16x16x128_f8f6f4 v[76:79], v[156:163], v[40:47], v[202:205], v154, v154 op_sel_hi:[0,0,0]
	s_setprio 0
	s_barrier
	v_mov_b32_e32 v128, v147
	ds_read_b128 v[24:27], v153 offset:49152
	ds_read_b128 v[28:31], v153 offset:50176
	ds_read_b128 v[164:167], v153 offset:51200
	ds_read_b128 v[168:171], v153 offset:52224
	ds_read_b128 v[178:181], v153 offset:53248
	ds_read_b128 v[182:185], v153 offset:54272
	ds_read_b128 v[186:189], v153 offset:55296
	ds_read_b128 v[190:193], v153 offset:56320
	s_add_i32 s0, s52, s66
	v_lshl_add_u64 v[16:17], s[62:63], 0, v[128:129]
	v_lshl_add_u64 v[16:17], v[16:17], 0, s[40:41]
	s_mov_b32 m0, s0
	v_mov_b32_e32 v128, v149
	global_load_lds_dwordx4 v[16:17], off
	s_add_i32 m0, s0, 0x2000
	v_lshl_add_u64 v[16:17], s[62:63], 0, v[128:129]
	v_lshl_add_u64 v[16:17], v[16:17], 0, s[40:41]
	s_add_u32 s0, s62, 0x18080
	global_load_lds_dwordx4 v[16:17], off
	s_addc_u32 s1, s63, 0
	v_mov_b32_e32 v16, v147
	s_add_i32 s52, s53, s66
	s_mov_b32 m0, s52
	v_mov_b32_e32 v128, v146
	global_load_lds_dwordx4 v16, s[0:1]
	v_mov_b32_e32 v16, v149
	s_add_i32 m0, s52, 0x2000
	s_nop 0
	global_load_lds_dwordx4 v16, s[0:1]
	s_mov_b32 m0, s75
	v_lshl_add_u64 v[16:17], s[64:65], 0, v[128:129]
	v_lshl_add_u64 v[16:17], v[16:17], 0, s[40:41]
	v_mov_b32_e32 v128, v148
	global_load_lds_dwordx4 v[16:17], off
	s_mov_b32 m0, s77
	v_lshl_add_u64 v[16:17], s[64:65], 0, v[128:129]
	v_lshl_add_u64 v[16:17], v[16:17], 0, s[40:41]
	global_load_lds_dwordx4 v[16:17], off
	s_waitcnt vmcnt(8)
	s_waitcnt lgkmcnt(0)
	s_barrier
	s_setprio 1
	v_mfma_scale_f32_16x16x128_f8f6f4 v[48:51], v[0:7], v[24:31], v[48:51], v154, v154 op_sel_hi:[0,0,0]
	v_mfma_scale_f32_16x16x128_f8f6f4 v[52:55], v[8:15], v[24:31], v[52:55], v154, v154 op_sel_hi:[0,0,0]
	v_mfma_scale_f32_16x16x128_f8f6f4 v[32:35], v[0:7], v[164:171], v[206:209], v154, v154 op_sel_hi:[0,0,0]
	v_mfma_scale_f32_16x16x128_f8f6f4 v[36:39], v[8:15], v[164:171], v[210:213], v154, v154 op_sel_hi:[0,0,0]
	v_mfma_scale_f32_16x16x128_f8f6f4 v[16:19], v[0:7], v[178:185], v[214:217], v154, v154 op_sel_hi:[0,0,0]
	v_mfma_scale_f32_16x16x128_f8f6f4 v[20:23], v[8:15], v[178:185], v[218:221], v154, v154 op_sel_hi:[0,0,0]
	v_mfma_scale_f32_16x16x128_f8f6f4 v[4:7], v[0:7], v[186:193], v[226:229], v154, v154 op_sel_hi:[0,0,0]
	v_mfma_scale_f32_16x16x128_f8f6f4 v[8:11], v[8:15], v[186:193], v[230:233], v154, v154 op_sel_hi:[0,0,0]
	v_mfma_scale_f32_16x16x128_f8f6f4 v[56:59], v[134:141], v[24:31], v[56:59], v154, v154 op_sel_hi:[0,0,0]
	v_mfma_scale_f32_16x16x128_f8f6f4 v[60:63], v[156:163], v[24:31], v[60:63], v154, v154 op_sel_hi:[0,0,0]
	v_mfma_scale_f32_16x16x128_f8f6f4 v[40:43], v[134:141], v[164:171], v[234:237], v154, v154 op_sel_hi:[0,0,0]
	v_mfma_scale_f32_16x16x128_f8f6f4 v[44:47], v[156:163], v[164:171], v[238:241], v154, v154 op_sel_hi:[0,0,0]
	v_mfma_scale_f32_16x16x128_f8f6f4 v[24:27], v[134:141], v[178:185], v[242:245], v154, v154 op_sel_hi:[0,0,0]
	v_mfma_scale_f32_16x16x128_f8f6f4 v[28:31], v[156:163], v[178:185], v[246:249], v154, v154 op_sel_hi:[0,0,0]
	v_mfma_scale_f32_16x16x128_f8f6f4 v[12:15], v[134:141], v[186:193], v[250:253], v154, v154 op_sel_hi:[0,0,0]
	v_mfma_scale_f32_16x16x128_f8f6f4 v[0:3], v[156:163], v[186:193], v[130:133], v154, v154 op_sel_hi:[0,0,0]
	s_setprio 0
	s_barrier
	s_add_i32 s91, s91, 2
	s_add_u32 s10, s10, 0x100
	s_addc_u32 s11, s11, 0
	s_add_u32 s89, s89, 0x100
	s_addc_u32 s90, s90, 0
	s_cmp_gt_u32 s91, 3
	s_cbranch_scc1 .LBB0_308

; #define PG8_STAGE(bufoff, gbase, voff) do { _Pragma("unroll") for (int _i = 0; _i < 2; ++_i) { unsigned vo_ = (voff)[_i]; if constexpr (FP8) asm volatile("" : "+v"(vo_)); \
;         __builtin_amdgcn_global_load_lds((const unsigned*)((const char*)(gbase) + vo_), (PG8_LAS unsigned*)(lds + (bufoff) + ldsw + _i * 8192), 16, 0, 0); } } while (0)
; #define PG8_LDA(dst, b, h) do { _Pragma("unroll") for (int m = 0; m < 4; ++m) _Pragma("unroll") for (int k = 0; k < 2; ++k) dst[m][k] = *(const PG8_LAS bf16x8*)(lds + PG8_SA(b, h) + aoff + m * 2048 + k * 1024); } while (0)
; #define PG8_LDB(dst, b, h) do { _Pragma("unroll") for (int n = 0; n < 2; ++n) _Pragma("unroll") for (int k = 0; k < 2; ++k) dst[n][k] = *(const PG8_LAS bf16x8*)(lds + PG8_SB(b, h) + boff + n * 2048 + k * 1024); } while (0)
; #define PG8_WAIT_V(n) asm volatile("s_waitcnt vmcnt(" #n ")" ::: "memory")
; #define PG8_WAIT_L(n) asm volatile("s_waitcnt lgkmcnt(" #n ")" ::: "memory")
; #define PG8_BAR __builtin_amdgcn_s_barrier()
; #define PG8_SCHED __builtin_amdgcn_sched_barrier(0)
; template <class Epi, class Sched, bool ALIGN_EPI = false, bool SP2 = false, bool FP8 = false>
; __device__ __forceinline__ void gemm_phase(PG8_LAS unsigned char* lds, const Gemm g, const Sched& S, const Epi& E) {
;     ...
;             const bool last = (t == nt - 2);
;             const char* a1 = cA + (size_t)(t + 1) * kstep;
;             const char* a2 = last ? nA : cA + (size_t)(t + 2) * kstep; const char* b2 = last ? nB : cB + (size_t)(t + 2) * kstep;
;             const char* a3 = a2 + kstep; const char* b3 = b2 + kstep;
;             if (last && has_next) S.a_ready(nxt);
;             if constexpr (SP2) {
;             PG8_LDB(B0, 0, 0); PG8_LDB(B1, 0, 1); PG8_SCHED; PG8_LDA(At, 0, 0); PG8_STAGE(PG8_SA(1, 1), a1 + hstep, voffA);
;             PG8_WAIT_V(8); PG8_WAIT_L(0); PG8_BAR; PG8_MMA(0, 0, At, B0); PG8_MMA(0, 1, At, B1); PG8_BAR; PG8_SCHED;
;             PG8_LDA(At, 0, 1); PG8_STAGE(PG8_SB(0, 0), b2, voffB); PG8_STAGE(PG8_SB(0, 1), b2 + hstep, voffB); PG8_STAGE(PG8_SA(0, 0), a2, voffA);
;             PG8_WAIT_V(8); PG8_WAIT_L(0); PG8_BAR; PG8_MMA(1, 0, At, B0); PG8_MMA(1, 1, At, B1); PG8_BAR; PG8_SCHED;
.Lmy_nobar_P4:
.LBB0_342:
	v_add_u32_e32 v140, s69, v201
	v_add_u32_e32 v156, s70, v201
	ds_read_b128 v[128:131], v140
	ds_read_b128 v[132:135], v140 offset:1024
	ds_read_b128 v[136:139], v140 offset:2048
	ds_read_b128 v[140:143], v140 offset:3072
	ds_read_b128 v[144:147], v156
	ds_read_b128 v[148:151], v156 offset:1024
	ds_read_b128 v[152:155], v156 offset:2048
	ds_read_b128 v[156:159], v156 offset:3072
	s_add_u32 s0, s10, 0xfffe0080
	s_addc_u32 s1, s11, -1
	s_cmp_eq_u32 s74, 4
	s_cselect_b32 s55, s9, s1
	s_cselect_b32 s54, s45, s0
	s_cselect_b32 s57, s43, s73
	s_cselect_b32 s56, s51, s72
	v_mov_b32_e32 v178, v197
	ds_read_b128 v[160:163], v202
	ds_read_b128 v[164:167], v202 offset:1024
	ds_read_b128 v[168:171], v202 offset:2048
	ds_read_b128 v[172:175], v202 offset:3072
	ds_read_b128 v[184:187], v202 offset:4096
	ds_read_b128 v[188:191], v202 offset:5120
	ds_read_b128 v[206:209], v202 offset:6144
	ds_read_b128 v[210:213], v202 offset:7168
	s_add_i32 m0, s53, 0xc000
	s_nop 0
	global_load_lds_dwordx4 v178, s[10:11]
	v_mov_b32_e32 v178, v199
	s_add_i32 m0, s53, 0xe000
	s_nop 0
	global_load_lds_dwordx4 v178, s[10:11]
	s_waitcnt vmcnt(8)
	s_waitcnt lgkmcnt(0)
	s_barrier
	s_setprio 1
	v_mfma_scale_f32_16x16x128_f8f6f4 v[116:119], v[128:135], v[160:167], v[116:119], v203, v203 op_sel_hi:[0,0,0]
	v_mfma_scale_f32_16x16x128_f8f6f4 v[112:115], v[136:143], v[160:167], v[112:115], v203, v203 op_sel_hi:[0,0,0]
	v_mfma_scale_f32_16x16x128_f8f6f4 v[108:111], v[128:135], v[168:175], v[108:111], v203, v203 op_sel_hi:[0,0,0]
	v_mfma_scale_f32_16x16x128_f8f6f4 v[100:103], v[136:143], v[168:175], v[100:103], v203, v203 op_sel_hi:[0,0,0]
	v_mfma_scale_f32_16x16x128_f8f6f4 v[192:195], v[128:135], v[184:191], v[92:95], v203, v203 op_sel_hi:[0,0,0]
	v_mfma_scale_f32_16x16x128_f8f6f4 v[214:217], v[136:143], v[184:191], v[84:87], v203, v203 op_sel_hi:[0,0,0]
	v_mfma_scale_f32_16x16x128_f8f6f4 v[218:221], v[128:135], v[206:213], v[76:79], v203, v203 op_sel_hi:[0,0,0]
	v_mfma_scale_f32_16x16x128_f8f6f4 v[222:225], v[136:143], v[206:213], v[68:71], v203, v203 op_sel_hi:[0,0,0]
	v_mfma_scale_f32_16x16x128_f8f6f4 v[124:127], v[144:151], v[160:167], v[124:127], v203, v203 op_sel_hi:[0,0,0]
	v_mfma_scale_f32_16x16x128_f8f6f4 v[120:123], v[152:159], v[160:167], v[120:123], v203, v203 op_sel_hi:[0,0,0]
	v_mfma_scale_f32_16x16x128_f8f6f4 v[104:107], v[144:151], v[168:175], v[104:107], v203, v203 op_sel_hi:[0,0,0]
	v_mfma_scale_f32_16x16x128_f8f6f4 v[96:99], v[152:159], v[168:175], v[96:99], v203, v203 op_sel_hi:[0,0,0]
	v_mfma_scale_f32_16x16x128_f8f6f4 v[160:163], v[144:151], v[184:191], v[88:91], v203, v203 op_sel_hi:[0,0,0]
	v_mfma_scale_f32_16x16x128_f8f6f4 v[164:167], v[152:159], v[184:191], v[80:83], v203, v203 op_sel_hi:[0,0,0]
	v_mfma_scale_f32_16x16x128_f8f6f4 v[168:171], v[144:151], v[206:213], v[72:75], v203, v203 op_sel_hi:[0,0,0]
	v_mfma_scale_f32_16x16x128_f8f6f4 v[172:175], v[152:159], v[206:213], v[64:67], v203, v203 op_sel_hi:[0,0,0]
	s_setprio 0
	s_barrier
	v_mov_b32_e32 v178, v198
	s_add_i32 s0, s69, s41
	s_nop 2
	ds_read_b128 v[64:67], v202 offset:16384
	ds_read_b128 v[68:71], v202 offset:17408
	ds_read_b128 v[72:75], v202 offset:18432
	ds_read_b128 v[76:79], v202 offset:19456
	ds_read_b128 v[80:83], v202 offset:20480
	ds_read_b128 v[84:87], v202 offset:21504
	ds_read_b128 v[88:91], v202 offset:22528
	ds_read_b128 v[92:95], v202 offset:23552
	s_mov_b32 m0, s0
	s_nop 0
	global_load_lds_dwordx4 v178, s[56:57]
	v_mov_b32_e32 v178, v200
	s_add_i32 m0, s0, 0x2000
	s_add_u32 s0, s56, 0x20000
	global_load_lds_dwordx4 v178, s[56:57]
	s_addc_u32 s1, s57, 0
	v_mov_b32_e32 v178, v198
	s_add_i32 s75, s70, s41
	s_mov_b32 m0, s75
	s_nop 0
	global_load_lds_dwordx4 v178, s[0:1]
	v_mov_b32_e32 v178, v200
	s_add_i32 m0, s75, 0x2000
	s_nop 0
	global_load_lds_dwordx4 v178, s[0:1]
	v_mov_b32_e32 v178, v197
	s_mov_b32 m0, s53
	s_nop 0
	global_load_lds_dwordx4 v178, s[54:55]
	v_mov_b32_e32 v178, v199
	s_mov_b32 m0, s58
	s_nop 0
	global_load_lds_dwordx4 v178, s[54:55]
	s_waitcnt vmcnt(8)
	s_waitcnt lgkmcnt(0)
	s_barrier
	s_setprio 1
	v_mfma_scale_f32_16x16x128_f8f6f4 v[52:55], v[128:135], v[64:71], v[52:55], v203, v203 op_sel_hi:[0,0,0]
	v_mfma_scale_f32_16x16x128_f8f6f4 v[48:51], v[136:143], v[64:71], v[48:51], v203, v203 op_sel_hi:[0,0,0]
	v_mfma_scale_f32_16x16x128_f8f6f4 v[44:47], v[128:135], v[72:79], v[44:47], v203, v203 op_sel_hi:[0,0,0]
	v_mfma_scale_f32_16x16x128_f8f6f4 v[184:187], v[136:143], v[72:79], v[36:39], v203, v203 op_sel_hi:[0,0,0]
	v_mfma_scale_f32_16x16x128_f8f6f4 v[188:191], v[128:135], v[80:87], v[28:31], v203, v203 op_sel_hi:[0,0,0]
	v_mfma_scale_f32_16x16x128_f8f6f4 v[206:209], v[136:143], v[80:87], v[20:23], v203, v203 op_sel_hi:[0,0,0]
	v_mfma_scale_f32_16x16x128_f8f6f4 v[210:213], v[128:135], v[88:95], v[12:15], v203, v203 op_sel_hi:[0,0,0]
	v_mfma_scale_f32_16x16x128_f8f6f4 v[226:229], v[136:143], v[88:95], v[4:7], v203, v203 op_sel_hi:[0,0,0]
	v_mfma_scale_f32_16x16x128_f8f6f4 v[40:43], v[144:151], v[72:79], v[40:43], v203, v203 op_sel_hi:[0,0,0]
	v_mfma_scale_f32_16x16x128_f8f6f4 v[230:233], v[144:151], v[64:71], v[60:63], v203, v203 op_sel_hi:[0,0,0]
	v_mfma_scale_f32_16x16x128_f8f6f4 v[234:237], v[152:159], v[64:71], v[56:59], v203, v203 op_sel_hi:[0,0,0]
	v_mfma_scale_f32_16x16x128_f8f6f4 v[238:241], v[152:159], v[72:79], v[32:35], v203, v203 op_sel_hi:[0,0,0]
	v_mfma_scale_f32_16x16x128_f8f6f4 v[242:245], v[144:151], v[80:87], v[24:27], v203, v203 op_sel_hi:[0,0,0]
	v_mfma_scale_f32_16x16x128_f8f6f4 v[246:249], v[152:159], v[80:87], v[16:19], v203, v203 op_sel_hi:[0,0,0]
	v_mfma_scale_f32_16x16x128_f8f6f4 v[250:253], v[144:151], v[88:95], v[8:11], v203, v203 op_sel_hi:[0,0,0]
	v_mfma_scale_f32_16x16x128_f8f6f4 v[180:183], v[152:159], v[88:95], v[0:3], v203, v203 op_sel_hi:[0,0,0]
	s_setprio 0
	s_barrier
; #define PG8_STAGE(bufoff, gbase, voff) do { _Pragma("unroll") for (int _i = 0; _i < 2; ++_i) { unsigned vo_ = (voff)[_i]; if constexpr (FP8) asm volatile("" : "+v"(vo_)); \
;         __builtin_amdgcn_global_load_lds((const unsigned*)((const char*)(gbase) + vo_), (PG8_LAS unsigned*)(lds + (bufoff) + ldsw + _i * 8192), 16, 0, 0); } } while (0)
; #define PG8_LDA(dst, b, h) do { _Pragma("unroll") for (int m = 0; m < 4; ++m) _Pragma("unroll") for (int k = 0; k < 2; ++k) dst[m][k] = *(const PG8_LAS bf16x8*)(lds + PG8_SA(b, h) + aoff + m * 2048 + k * 1024); } while (0)
; #define PG8_LDB(dst, b, h) do { _Pragma("unroll") for (int n = 0; n < 2; ++n) _Pragma("unroll") for (int k = 0; k < 2; ++k) dst[n][k] = *(const PG8_LAS bf16x8*)(lds + PG8_SB(b, h) + boff + n * 2048 + k * 1024); } while (0)
; #define PG8_WAIT_V(n) asm volatile("s_waitcnt vmcnt(" #n ")" ::: "memory")
; #define PG8_WAIT_L(n) asm volatile("s_waitcnt lgkmcnt(" #n ")" ::: "memory")
; #define PG8_BAR __builtin_amdgcn_s_barrier()
; #define PG8_SCHED __builtin_amdgcn_sched_barrier(0)
; template <class Epi, class Sched, bool ALIGN_EPI = false, bool SP2 = false, bool FP8 = false>
; __device__ __forceinline__ void gemm_phase(PG8_LAS unsigned char* lds, const Gemm g, const Sched& S, const Epi& E) {
;     ...
;             PG8_LDB(B0, 1, 0); PG8_LDB(B1, 1, 1); PG8_SCHED; PG8_LDA(At, 1, 0); PG8_STAGE(PG8_SA(0, 1), a2 + hstep, voffA);
;             PG8_WAIT_V(8); PG8_WAIT_L(0); PG8_BAR; PG8_MMA(0, 0, At, B0); PG8_MMA(0, 1, At, B1); PG8_BAR; PG8_SCHED;
;             PG8_LDA(At, 1, 1); PG8_STAGE(PG8_SB(1, 0), b3, voffB); PG8_STAGE(PG8_SB(1, 1), b3 + hstep, voffB); PG8_STAGE(PG8_SA(1, 0), a3, voffA);
;             PG8_WAIT_V(8); PG8_WAIT_L(0); PG8_BAR; PG8_MMA(1, 0, At, B0); PG8_MMA(1, 1, At, B1); PG8_BAR; PG8_SCHED;
	s_add_i32 s75, 0, 0x18000
	s_nop 2
	v_add_u32_e32 v8, s75, v201
	s_add_i32 s77, 0, 0x1c000
	ds_read_b128 v[0:3], v8
	ds_read_b128 v[4:7], v8 offset:1024
	ds_read_b128 v[56:59], v8 offset:2048
	ds_read_b128 v[60:63], v8 offset:3072
	v_add_u32_e32 v8, s77, v201
	ds_read_b128 v[128:131], v8
	ds_read_b128 v[132:135], v8 offset:1024
	ds_read_b128 v[136:139], v8 offset:2048
	ds_read_b128 v[140:143], v8 offset:3072
	s_add_u32 s0, s54, 0x20000
	v_mov_b32_e32 v64, v197
	s_mov_b32 m0, s59
	ds_read_b128 v[8:11], v202 offset:32768
	ds_read_b128 v[12:15], v202 offset:33792
	ds_read_b128 v[16:19], v202 offset:34816
	ds_read_b128 v[20:23], v202 offset:35840
	ds_read_b128 v[24:27], v202 offset:36864
	ds_read_b128 v[28:31], v202 offset:37888
	ds_read_b128 v[32:35], v202 offset:38912
	ds_read_b128 v[36:39], v202 offset:39936
	s_addc_u32 s1, s55, 0
	s_nop 0
	global_load_lds_dwordx4 v64, s[0:1]
	v_mov_b32_e32 v64, v199
	s_mov_b32 m0, s60
	s_nop 0
	global_load_lds_dwordx4 v64, s[0:1]
	s_waitcnt vmcnt(8)
	s_waitcnt lgkmcnt(0)
	s_barrier
	s_setprio 1
	v_mfma_scale_f32_16x16x128_f8f6f4 v[116:119], v[0:7], v[8:15], v[116:119], v203, v203 op_sel_hi:[0,0,0]
	v_mfma_scale_f32_16x16x128_f8f6f4 v[112:115], v[56:63], v[8:15], v[112:115], v203, v203 op_sel_hi:[0,0,0]
	v_mfma_scale_f32_16x16x128_f8f6f4 v[108:111], v[0:7], v[16:23], v[108:111], v203, v203 op_sel_hi:[0,0,0]
	v_mfma_scale_f32_16x16x128_f8f6f4 v[100:103], v[56:63], v[16:23], v[100:103], v203, v203 op_sel_hi:[0,0,0]
	v_mfma_scale_f32_16x16x128_f8f6f4 v[92:95], v[0:7], v[24:31], v[192:195], v203, v203 op_sel_hi:[0,0,0]
	v_mfma_scale_f32_16x16x128_f8f6f4 v[84:87], v[56:63], v[24:31], v[214:217], v203, v203 op_sel_hi:[0,0,0]
	v_mfma_scale_f32_16x16x128_f8f6f4 v[76:79], v[0:7], v[32:39], v[218:221], v203, v203 op_sel_hi:[0,0,0]
	v_mfma_scale_f32_16x16x128_f8f6f4 v[68:71], v[56:63], v[32:39], v[222:225], v203, v203 op_sel_hi:[0,0,0]
	v_mfma_scale_f32_16x16x128_f8f6f4 v[124:127], v[128:135], v[8:15], v[124:127], v203, v203 op_sel_hi:[0,0,0]
	v_mfma_scale_f32_16x16x128_f8f6f4 v[120:123], v[136:143], v[8:15], v[120:123], v203, v203 op_sel_hi:[0,0,0]
	v_mfma_scale_f32_16x16x128_f8f6f4 v[104:107], v[128:135], v[16:23], v[104:107], v203, v203 op_sel_hi:[0,0,0]
	v_mfma_scale_f32_16x16x128_f8f6f4 v[96:99], v[136:143], v[16:23], v[96:99], v203, v203 op_sel_hi:[0,0,0]
	v_mfma_scale_f32_16x16x128_f8f6f4 v[88:91], v[128:135], v[24:31], v[160:163], v203, v203 op_sel_hi:[0,0,0]
	v_mfma_scale_f32_16x16x128_f8f6f4 v[80:83], v[136:143], v[24:31], v[164:167], v203, v203 op_sel_hi:[0,0,0]
	v_mfma_scale_f32_16x16x128_f8f6f4 v[72:75], v[128:135], v[32:39], v[168:171], v203, v203 op_sel_hi:[0,0,0]
	v_mfma_scale_f32_16x16x128_f8f6f4 v[64:67], v[136:143], v[32:39], v[172:175], v203, v203 op_sel_hi:[0,0,0]
	s_setprio 0
	s_barrier
	v_mov_b32_e32 v178, v198
	ds_read_b128 v[144:147], v202 offset:49152
	ds_read_b128 v[148:151], v202 offset:50176
	ds_read_b128 v[152:155], v202 offset:51200
	ds_read_b128 v[156:159], v202 offset:52224
	ds_read_b128 v[160:163], v202 offset:53248
	ds_read_b128 v[164:167], v202 offset:54272
	ds_read_b128 v[168:171], v202 offset:55296
	ds_read_b128 v[172:175], v202 offset:56320
	s_add_i32 s0, s75, s41
	v_lshl_add_u64 v[8:9], s[56:57], 0, v[178:179]
	v_lshl_add_u64 v[8:9], v[8:9], 0, s[14:15]
	s_mov_b32 m0, s0
	v_mov_b32_e32 v178, v200
	global_load_lds_dwordx4 v[8:9], off
	s_add_i32 m0, s0, 0x2000
	v_lshl_add_u64 v[8:9], s[56:57], 0, v[178:179]
	v_lshl_add_u64 v[8:9], v[8:9], 0, s[14:15]
	s_add_u32 s0, s56, 0x20080
	global_load_lds_dwordx4 v[8:9], off
	s_addc_u32 s1, s57, 0
	v_mov_b32_e32 v8, v198
	s_add_i32 s56, s77, s41
	s_mov_b32 m0, s56
	v_mov_b32_e32 v178, v197
	global_load_lds_dwordx4 v8, s[0:1]
	v_mov_b32_e32 v8, v200
	s_add_i32 m0, s56, 0x2000
	s_nop 0
	global_load_lds_dwordx4 v8, s[0:1]
	s_mov_b32 m0, s66
	v_lshl_add_u64 v[8:9], s[54:55], 0, v[178:179]
	v_lshl_add_u64 v[8:9], v[8:9], 0, s[14:15]
	v_mov_b32_e32 v178, v199
	global_load_lds_dwordx4 v[8:9], off
	s_mov_b32 m0, s67
	v_lshl_add_u64 v[8:9], s[54:55], 0, v[178:179]
	v_lshl_add_u64 v[8:9], v[8:9], 0, s[14:15]
	global_load_lds_dwordx4 v[8:9], off
	s_waitcnt vmcnt(8)
	s_waitcnt lgkmcnt(0)
	s_barrier
	s_setprio 1
	v_mfma_scale_f32_16x16x128_f8f6f4 v[52:55], v[0:7], v[144:151], v[52:55], v203, v203 op_sel_hi:[0,0,0]
	v_mfma_scale_f32_16x16x128_f8f6f4 v[48:51], v[56:63], v[144:151], v[48:51], v203, v203 op_sel_hi:[0,0,0]
	v_mfma_scale_f32_16x16x128_f8f6f4 v[44:47], v[0:7], v[152:159], v[44:47], v203, v203 op_sel_hi:[0,0,0]
	v_mfma_scale_f32_16x16x128_f8f6f4 v[36:39], v[56:63], v[152:159], v[184:187], v203, v203 op_sel_hi:[0,0,0]
	v_mfma_scale_f32_16x16x128_f8f6f4 v[28:31], v[0:7], v[160:167], v[188:191], v203, v203 op_sel_hi:[0,0,0]
	v_mfma_scale_f32_16x16x128_f8f6f4 v[20:23], v[56:63], v[160:167], v[206:209], v203, v203 op_sel_hi:[0,0,0]
	v_mfma_scale_f32_16x16x128_f8f6f4 v[12:15], v[0:7], v[168:175], v[210:213], v203, v203 op_sel_hi:[0,0,0]
	v_mfma_scale_f32_16x16x128_f8f6f4 v[4:7], v[56:63], v[168:175], v[226:229], v203, v203 op_sel_hi:[0,0,0]
	v_mfma_scale_f32_16x16x128_f8f6f4 v[60:63], v[128:135], v[144:151], v[230:233], v203, v203 op_sel_hi:[0,0,0]
	v_mfma_scale_f32_16x16x128_f8f6f4 v[56:59], v[136:143], v[144:151], v[234:237], v203, v203 op_sel_hi:[0,0,0]
	v_mfma_scale_f32_16x16x128_f8f6f4 v[40:43], v[128:135], v[152:159], v[40:43], v203, v203 op_sel_hi:[0,0,0]
	v_mfma_scale_f32_16x16x128_f8f6f4 v[32:35], v[136:143], v[152:159], v[238:241], v203, v203 op_sel_hi:[0,0,0]
	v_mfma_scale_f32_16x16x128_f8f6f4 v[24:27], v[128:135], v[160:167], v[242:245], v203, v203 op_sel_hi:[0,0,0]
	v_mfma_scale_f32_16x16x128_f8f6f4 v[16:19], v[136:143], v[160:167], v[246:249], v203, v203 op_sel_hi:[0,0,0]
	v_mfma_scale_f32_16x16x128_f8f6f4 v[8:11], v[128:135], v[168:175], v[250:253], v203, v203 op_sel_hi:[0,0,0]
	v_mfma_scale_f32_16x16x128_f8f6f4 v[0:3], v[136:143], v[168:175], v[180:183], v203, v203 op_sel_hi:[0,0,0]
	s_setprio 0
	s_barrier
	s_add_i32 s74, s74, 2
	s_add_u32 s10, s10, 0x100
	s_addc_u32 s11, s11, 0
	s_add_u32 s72, s72, 0x100
	s_addc_u32 s73, s73, 0
	s_cmp_gt_u32 s74, 5
	s_cbranch_scc0 .LBB0_342
	s_and_b64 vcc, exec, s[38:39]
	s_cbranch_vccz .LBB0_345

; #define PG8_STAGE(bufoff, gbase, voff) do { _Pragma("unroll") for (int _i = 0; _i < 2; ++_i) { unsigned vo_ = (voff)[_i]; if constexpr (FP8) asm volatile("" : "+v"(vo_)); \
;         __builtin_amdgcn_global_load_lds((const unsigned*)((const char*)(gbase) + vo_), (PG8_LAS unsigned*)(lds + (bufoff) + ldsw + _i * 8192), 16, 0, 0); } } while (0)
; #define PG8_LDA(dst, b, h) do { _Pragma("unroll") for (int m = 0; m < 4; ++m) _Pragma("unroll") for (int k = 0; k < 2; ++k) dst[m][k] = *(const PG8_LAS bf16x8*)(lds + PG8_SA(b, h) + aoff + m * 2048 + k * 1024); } while (0)
; #define PG8_LDB(dst, b, h) do { _Pragma("unroll") for (int n = 0; n < 2; ++n) _Pragma("unroll") for (int k = 0; k < 2; ++k) dst[n][k] = *(const PG8_LAS bf16x8*)(lds + PG8_SB(b, h) + boff + n * 2048 + k * 1024); } while (0)
; #define PG8_WAIT_V(n) asm volatile("s_waitcnt vmcnt(" #n ")" ::: "memory")
; #define PG8_WAIT_L(n) asm volatile("s_waitcnt lgkmcnt(" #n ")" ::: "memory")
; #define PG8_BAR __builtin_amdgcn_s_barrier()
; #define PG8_SCHED __builtin_amdgcn_sched_barrier(0)
; template <class Epi, class Sched, bool ALIGN_EPI = false, bool SP2 = false, bool FP8 = false>
; __device__ __forceinline__ void gemm_phase(PG8_LAS unsigned char* lds, const Gemm g, const Sched& S, const Epi& E) {
;     ...
;             const bool last = (t == nt - 2);
;             const char* a1 = cA + (size_t)(t + 1) * kstep;
;             const char* a2 = last ? nA : cA + (size_t)(t + 2) * kstep; const char* b2 = last ? nB : cB + (size_t)(t + 2) * kstep;
;             const char* a3 = a2 + kstep; const char* b3 = b2 + kstep;
;             if (last && has_next) S.a_ready(nxt);
;             if constexpr (SP2) {
;             PG8_LDB(B0, 0, 0); PG8_LDB(B1, 0, 1); PG8_SCHED; PG8_LDA(At, 0, 0); PG8_STAGE(PG8_SA(1, 1), a1 + hstep, voffA);
;             PG8_WAIT_V(8); PG8_WAIT_L(0); PG8_BAR; PG8_MMA(0, 0, At, B0); PG8_MMA(0, 1, At, B1); PG8_BAR; PG8_SCHED;
;             PG8_LDA(At, 0, 1); PG8_STAGE(PG8_SB(0, 0), b2, voffB); PG8_STAGE(PG8_SB(0, 1), b2 + hstep, voffB); PG8_STAGE(PG8_SA(0, 0), a2, voffA);
;             PG8_WAIT_V(8); PG8_WAIT_L(0); PG8_BAR; PG8_MMA(1, 0, At, B0); PG8_MMA(1, 1, At, B1); PG8_BAR; PG8_SCHED;
.Lmy_nobar_P5:
.LBB0_391:
	ds_read_b128 v[146:149], v153
	ds_read_b128 v[158:161], v153 offset:1024
	ds_read_b128 v[162:165], v153 offset:2048
	ds_read_b128 v[166:169], v153 offset:3072
	ds_read_b128 v[170:173], v154
	ds_read_b128 v[174:177], v154 offset:1024
	ds_read_b128 v[178:181], v154 offset:2048
	ds_read_b128 v[182:185], v154 offset:3072
	s_add_u32 s0, s40, 0xfffc0080
	s_addc_u32 s1, s41, -1
	s_cmp_eq_u32 s61, 12
	s_cselect_b32 s45, s15, s1
	s_cselect_b32 s44, s57, s0
	s_cselect_b32 s43, s13, s60
	s_cselect_b32 s42, s58, s59
	v_lshl_add_u64 v[218:219], s[40:41], 0, v[138:139]
	s_add_i32 m0, s39, 0xc000
	ds_read_b128 v[186:189], v155
	ds_read_b128 v[190:193], v155 offset:1024
	ds_read_b128 v[194:197], v155 offset:2048
	ds_read_b128 v[198:201], v155 offset:3072
	ds_read_b128 v[202:205], v155 offset:4096
	ds_read_b128 v[206:209], v155 offset:5120
	ds_read_b128 v[210:213], v155 offset:6144
	ds_read_b128 v[214:217], v155 offset:7168
	global_load_lds_dwordx4 v[218:219], off
	v_lshl_add_u64 v[218:219], s[40:41], 0, v[140:141]
	s_add_i32 m0, s39, 0xe000
	s_nop 0
	global_load_lds_dwordx4 v[218:219], off
	s_waitcnt vmcnt(8)
	s_waitcnt lgkmcnt(0)
	s_barrier
	s_setprio 1
	v_mfma_f32_16x16x32_bf16 v[124:127], v[146:149], v[186:189], v[124:127]
	v_mfma_f32_16x16x32_bf16 v[120:123], v[162:165], v[186:189], v[120:123]
	v_mfma_f32_16x16x32_bf16 v[108:111], v[146:149], v[194:197], v[108:111]
	v_mfma_f32_16x16x32_bf16 v[104:107], v[162:165], v[194:197], v[104:107]
	v_mfma_f32_16x16x32_bf16 v[92:95], v[146:149], v[202:205], v[92:95]
	v_mfma_f32_16x16x32_bf16 v[88:91], v[162:165], v[202:205], v[88:91]
	v_mfma_f32_16x16x32_bf16 v[76:79], v[146:149], v[210:213], v[76:79]
	v_mfma_f32_16x16x32_bf16 v[72:75], v[162:165], v[210:213], v[72:75]
	v_mfma_f32_16x16x32_bf16 v[124:127], v[158:161], v[190:193], v[124:127]
	v_mfma_f32_16x16x32_bf16 v[120:123], v[166:169], v[190:193], v[120:123]
	v_mfma_f32_16x16x32_bf16 v[108:111], v[158:161], v[198:201], v[108:111]
	v_mfma_f32_16x16x32_bf16 v[104:107], v[166:169], v[198:201], v[104:107]
	v_mfma_f32_16x16x32_bf16 v[92:95], v[158:161], v[206:209], v[92:95]
	v_mfma_f32_16x16x32_bf16 v[88:91], v[166:169], v[206:209], v[88:91]
	v_mfma_f32_16x16x32_bf16 v[76:79], v[158:161], v[214:217], v[76:79]
	v_mfma_f32_16x16x32_bf16 v[72:75], v[166:169], v[214:217], v[72:75]
	v_mfma_f32_16x16x32_bf16 v[116:119], v[170:173], v[186:189], v[116:119]
	v_mfma_f32_16x16x32_bf16 v[112:115], v[178:181], v[186:189], v[112:115]
	v_mfma_f32_16x16x32_bf16 v[100:103], v[170:173], v[194:197], v[100:103]
	v_mfma_f32_16x16x32_bf16 v[96:99], v[178:181], v[194:197], v[96:99]
	v_mfma_f32_16x16x32_bf16 v[84:87], v[170:173], v[202:205], v[84:87]
	v_mfma_f32_16x16x32_bf16 v[80:83], v[178:181], v[202:205], v[80:83]
	v_mfma_f32_16x16x32_bf16 v[68:71], v[170:173], v[210:213], v[68:71]
	v_mfma_f32_16x16x32_bf16 v[64:67], v[178:181], v[210:213], v[64:67]
	v_mfma_f32_16x16x32_bf16 v[116:119], v[174:177], v[190:193], v[116:119]
	v_mfma_f32_16x16x32_bf16 v[112:115], v[182:185], v[190:193], v[112:115]
	v_mfma_f32_16x16x32_bf16 v[100:103], v[174:177], v[198:201], v[100:103]
	v_mfma_f32_16x16x32_bf16 v[96:99], v[182:185], v[198:201], v[96:99]
	v_mfma_f32_16x16x32_bf16 v[84:87], v[174:177], v[206:209], v[84:87]
	v_mfma_f32_16x16x32_bf16 v[80:83], v[182:185], v[206:209], v[80:83]
	v_mfma_f32_16x16x32_bf16 v[68:71], v[174:177], v[214:217], v[68:71]
	v_mfma_f32_16x16x32_bf16 v[64:67], v[182:185], v[214:217], v[64:67]
	s_setprio 0
	s_barrier
	s_add_i32 s0, s54, s46
	v_lshl_add_u64 v[218:219], s[42:43], 0, v[132:133]
	s_mov_b32 m0, s0
	ds_read_b128 v[186:189], v155 offset:16384
	ds_read_b128 v[190:193], v155 offset:17408
	ds_read_b128 v[194:197], v155 offset:18432
	ds_read_b128 v[198:201], v155 offset:19456
	ds_read_b128 v[202:205], v155 offset:20480
	ds_read_b128 v[206:209], v155 offset:21504
	ds_read_b128 v[210:213], v155 offset:22528
	ds_read_b128 v[214:217], v155 offset:23552
	global_load_lds_dwordx4 v[218:219], off
	s_add_i32 m0, s0, 0x2000
	s_add_u32 s0, s42, 0x40000
	v_lshl_add_u64 v[220:221], s[42:43], 0, v[128:129]
	s_addc_u32 s1, s43, 0
	s_add_i32 s62, s55, s46
	global_load_lds_dwordx4 v[220:221], off
	v_lshl_add_u64 v[222:223], s[0:1], 0, v[132:133]
	s_mov_b32 m0, s62
	v_lshl_add_u64 v[224:225], s[44:45], 0, v[130:131]
	global_load_lds_dwordx4 v[222:223], off
	v_lshl_add_u64 v[222:223], s[0:1], 0, v[128:129]
	s_add_i32 m0, s62, 0x2000
	s_nop 0
	global_load_lds_dwordx4 v[222:223], off
	v_lshl_add_u64 v[222:223], s[44:45], 0, v[134:135]
	s_mov_b32 m0, s39
	s_nop 0
	global_load_lds_dwordx4 v[222:223], off
	s_mov_b32 m0, s48
	s_nop 0
	global_load_lds_dwordx4 v[224:225], off
	s_waitcnt vmcnt(8)
	s_waitcnt lgkmcnt(0)
	s_barrier
; #define PG8_STAGE(bufoff, gbase, voff) do { _Pragma("unroll") for (int _i = 0; _i < 2; ++_i) { unsigned vo_ = (voff)[_i]; if constexpr (FP8) asm volatile("" : "+v"(vo_)); \
;         __builtin_amdgcn_global_load_lds((const unsigned*)((const char*)(gbase) + vo_), (PG8_LAS unsigned*)(lds + (bufoff) + ldsw + _i * 8192), 16, 0, 0); } } while (0)
; #define PG8_LDA(dst, b, h) do { _Pragma("unroll") for (int m = 0; m < 4; ++m) _Pragma("unroll") for (int k = 0; k < 2; ++k) dst[m][k] = *(const PG8_LAS bf16x8*)(lds + PG8_SA(b, h) + aoff + m * 2048 + k * 1024); } while (0)
; #define PG8_LDB(dst, b, h) do { _Pragma("unroll") for (int n = 0; n < 2; ++n) _Pragma("unroll") for (int k = 0; k < 2; ++k) dst[n][k] = *(const PG8_LAS bf16x8*)(lds + PG8_SB(b, h) + boff + n * 2048 + k * 1024); } while (0)
; #define PG8_WAIT_V(n) asm volatile("s_waitcnt vmcnt(" #n ")" ::: "memory")
; #define PG8_WAIT_L(n) asm volatile("s_waitcnt lgkmcnt(" #n ")" ::: "memory")
; #define PG8_BAR __builtin_amdgcn_s_barrier()
; #define PG8_SCHED __builtin_amdgcn_sched_barrier(0)
; template <class Epi, class Sched, bool ALIGN_EPI = false, bool SP2 = false, bool FP8 = false>
; __device__ __forceinline__ void gemm_phase(PG8_LAS unsigned char* lds, const Gemm g, const Sched& S, const Epi& E) {
;     ...
;             PG8_WAIT_V(8); PG8_WAIT_L(0); PG8_BAR; PG8_MMA(1, 0, At, B0); PG8_MMA(1, 1, At, B1); PG8_BAR; PG8_SCHED;
;             PG8_LDB(B0, 1, 0); PG8_LDB(B1, 1, 1); PG8_SCHED; PG8_LDA(At, 1, 0); PG8_STAGE(PG8_SA(0, 1), a2 + hstep, voffA);
;             PG8_WAIT_V(8); PG8_WAIT_L(0); PG8_BAR; PG8_MMA(0, 0, At, B0); PG8_MMA(0, 1, At, B1); PG8_BAR; PG8_SCHED;
	s_setprio 1
	v_mfma_f32_16x16x32_bf16 v[60:63], v[146:149], v[186:189], v[60:63]
	v_mfma_f32_16x16x32_bf16 v[56:59], v[162:165], v[186:189], v[56:59]
	v_mfma_f32_16x16x32_bf16 v[44:47], v[146:149], v[194:197], v[44:47]
	v_mfma_f32_16x16x32_bf16 v[40:43], v[162:165], v[194:197], v[40:43]
	v_mfma_f32_16x16x32_bf16 v[28:31], v[146:149], v[202:205], v[28:31]
	v_mfma_f32_16x16x32_bf16 v[24:27], v[162:165], v[202:205], v[24:27]
	v_mfma_f32_16x16x32_bf16 v[12:15], v[146:149], v[210:213], v[12:15]
	v_mfma_f32_16x16x32_bf16 v[8:11], v[162:165], v[210:213], v[8:11]
	v_mfma_f32_16x16x32_bf16 v[60:63], v[158:161], v[190:193], v[60:63]
	v_mfma_f32_16x16x32_bf16 v[56:59], v[166:169], v[190:193], v[56:59]
	v_mfma_f32_16x16x32_bf16 v[44:47], v[158:161], v[198:201], v[44:47]
	v_mfma_f32_16x16x32_bf16 v[40:43], v[166:169], v[198:201], v[40:43]
	v_mfma_f32_16x16x32_bf16 v[28:31], v[158:161], v[206:209], v[28:31]
	v_mfma_f32_16x16x32_bf16 v[24:27], v[166:169], v[206:209], v[24:27]
	v_mfma_f32_16x16x32_bf16 v[12:15], v[158:161], v[214:217], v[12:15]
	v_mfma_f32_16x16x32_bf16 v[8:11], v[166:169], v[214:217], v[8:11]
	v_mfma_f32_16x16x32_bf16 v[52:55], v[170:173], v[186:189], v[52:55]
	v_mfma_f32_16x16x32_bf16 v[48:51], v[178:181], v[186:189], v[48:51]
	v_mfma_f32_16x16x32_bf16 v[36:39], v[170:173], v[194:197], v[36:39]
	v_mfma_f32_16x16x32_bf16 v[32:35], v[178:181], v[194:197], v[32:35]
	v_mfma_f32_16x16x32_bf16 v[20:23], v[170:173], v[202:205], v[20:23]
	v_mfma_f32_16x16x32_bf16 v[16:19], v[178:181], v[202:205], v[16:19]
	v_mfma_f32_16x16x32_bf16 v[4:7], v[170:173], v[210:213], v[4:7]
	v_mfma_f32_16x16x32_bf16 v[0:3], v[178:181], v[210:213], v[0:3]
	v_mfma_f32_16x16x32_bf16 v[52:55], v[174:177], v[190:193], v[52:55]
	v_mfma_f32_16x16x32_bf16 v[48:51], v[182:185], v[190:193], v[48:51]
	v_mfma_f32_16x16x32_bf16 v[36:39], v[174:177], v[198:201], v[36:39]
	v_mfma_f32_16x16x32_bf16 v[32:35], v[182:185], v[198:201], v[32:35]
	v_mfma_f32_16x16x32_bf16 v[20:23], v[174:177], v[206:209], v[20:23]
	v_mfma_f32_16x16x32_bf16 v[16:19], v[182:185], v[206:209], v[16:19]
	v_mfma_f32_16x16x32_bf16 v[4:7], v[174:177], v[214:217], v[4:7]
	v_mfma_f32_16x16x32_bf16 v[0:3], v[182:185], v[214:217], v[0:3]
	s_setprio 0
	s_barrier
	s_add_i32 s62, 0, 0x18000
	s_add_i32 s63, 0, 0x1c000
	v_add_u32_e32 v166, s62, v151
	v_add_u32_e32 v182, s63, v151
	ds_read_b128 v[146:149], v166
	ds_read_b128 v[158:161], v166 offset:1024
	ds_read_b128 v[162:165], v166 offset:2048
	ds_read_b128 v[166:169], v166 offset:3072
	ds_read_b128 v[170:173], v182
	ds_read_b128 v[174:177], v182 offset:1024
	ds_read_b128 v[178:181], v182 offset:2048
	ds_read_b128 v[182:185], v182 offset:3072
	s_add_u32 s0, s44, 0x40000
	s_addc_u32 s1, s45, 0
	s_mov_b32 m0, s49
	v_lshl_add_u64 v[226:227], s[0:1], 0, v[134:135]
	ds_read_b128 v[186:189], v155 offset:32768
	ds_read_b128 v[190:193], v155 offset:33792
	ds_read_b128 v[194:197], v155 offset:34816
	ds_read_b128 v[198:201], v155 offset:35840
	ds_read_b128 v[202:205], v155 offset:36864
	ds_read_b128 v[206:209], v155 offset:37888
	ds_read_b128 v[210:213], v155 offset:38912
	ds_read_b128 v[214:217], v155 offset:39936
	global_load_lds_dwordx4 v[226:227], off
	v_lshl_add_u64 v[226:227], s[0:1], 0, v[130:131]
	s_mov_b32 m0, s50
	s_nop 0
	global_load_lds_dwordx4 v[226:227], off
	s_waitcnt vmcnt(8)
	s_waitcnt lgkmcnt(0)
	s_barrier
	s_setprio 1
	v_mfma_f32_16x16x32_bf16 v[124:127], v[146:149], v[186:189], v[124:127]
	v_mfma_f32_16x16x32_bf16 v[120:123], v[162:165], v[186:189], v[120:123]
	v_mfma_f32_16x16x32_bf16 v[108:111], v[146:149], v[194:197], v[108:111]
	v_mfma_f32_16x16x32_bf16 v[104:107], v[162:165], v[194:197], v[104:107]
	v_mfma_f32_16x16x32_bf16 v[92:95], v[146:149], v[202:205], v[92:95]
	v_mfma_f32_16x16x32_bf16 v[88:91], v[162:165], v[202:205], v[88:91]
	v_mfma_f32_16x16x32_bf16 v[76:79], v[146:149], v[210:213], v[76:79]
	v_mfma_f32_16x16x32_bf16 v[72:75], v[162:165], v[210:213], v[72:75]
	v_mfma_f32_16x16x32_bf16 v[124:127], v[158:161], v[190:193], v[124:127]
	v_mfma_f32_16x16x32_bf16 v[120:123], v[166:169], v[190:193], v[120:123]
	v_mfma_f32_16x16x32_bf16 v[108:111], v[158:161], v[198:201], v[108:111]
	v_mfma_f32_16x16x32_bf16 v[104:107], v[166:169], v[198:201], v[104:107]
	v_mfma_f32_16x16x32_bf16 v[92:95], v[158:161], v[206:209], v[92:95]
	v_mfma_f32_16x16x32_bf16 v[88:91], v[166:169], v[206:209], v[88:91]
	v_mfma_f32_16x16x32_bf16 v[76:79], v[158:161], v[214:217], v[76:79]
	v_mfma_f32_16x16x32_bf16 v[72:75], v[166:169], v[214:217], v[72:75]
	v_mfma_f32_16x16x32_bf16 v[116:119], v[170:173], v[186:189], v[116:119]
	v_mfma_f32_16x16x32_bf16 v[112:115], v[178:181], v[186:189], v[112:115]
	v_mfma_f32_16x16x32_bf16 v[100:103], v[170:173], v[194:197], v[100:103]
	v_mfma_f32_16x16x32_bf16 v[96:99], v[178:181], v[194:197], v[96:99]
	v_mfma_f32_16x16x32_bf16 v[84:87], v[170:173], v[202:205], v[84:87]
	v_mfma_f32_16x16x32_bf16 v[80:83], v[178:181], v[202:205], v[80:83]
	v_mfma_f32_16x16x32_bf16 v[68:71], v[170:173], v[210:213], v[68:71]
	v_mfma_f32_16x16x32_bf16 v[64:67], v[178:181], v[210:213], v[64:67]
	v_mfma_f32_16x16x32_bf16 v[116:119], v[174:177], v[190:193], v[116:119]
	v_mfma_f32_16x16x32_bf16 v[112:115], v[182:185], v[190:193], v[112:115]
	v_mfma_f32_16x16x32_bf16 v[100:103], v[174:177], v[198:201], v[100:103]
	v_mfma_f32_16x16x32_bf16 v[96:99], v[182:185], v[198:201], v[96:99]
	v_mfma_f32_16x16x32_bf16 v[84:87], v[174:177], v[206:209], v[84:87]
	v_mfma_f32_16x16x32_bf16 v[80:83], v[182:185], v[206:209], v[80:83]
	v_mfma_f32_16x16x32_bf16 v[68:71], v[174:177], v[214:217], v[68:71]
	v_mfma_f32_16x16x32_bf16 v[64:67], v[182:185], v[214:217], v[64:67]
	s_setprio 0
	s_barrier
; #define PG8_STAGE(bufoff, gbase, voff) do { _Pragma("unroll") for (int _i = 0; _i < 2; ++_i) { unsigned vo_ = (voff)[_i]; if constexpr (FP8) asm volatile("" : "+v"(vo_)); \
;         __builtin_amdgcn_global_load_lds((const unsigned*)((const char*)(gbase) + vo_), (PG8_LAS unsigned*)(lds + (bufoff) + ldsw + _i * 8192), 16, 0, 0); } } while (0)
; #define PG8_LDA(dst, b, h) do { _Pragma("unroll") for (int m = 0; m < 4; ++m) _Pragma("unroll") for (int k = 0; k < 2; ++k) dst[m][k] = *(const PG8_LAS bf16x8*)(lds + PG8_SA(b, h) + aoff + m * 2048 + k * 1024); } while (0)
; #define PG8_WAIT_V(n) asm volatile("s_waitcnt vmcnt(" #n ")" ::: "memory")
; #define PG8_WAIT_L(n) asm volatile("s_waitcnt lgkmcnt(" #n ")" ::: "memory")
; #define PG8_BAR __builtin_amdgcn_s_barrier()
; #define PG8_SCHED __builtin_amdgcn_sched_barrier(0)
; template <class Epi, class Sched, bool ALIGN_EPI = false, bool SP2 = false, bool FP8 = false>
; __device__ __forceinline__ void gemm_phase(PG8_LAS unsigned char* lds, const Gemm g, const Sched& S, const Epi& E) {
;     ...
;             PG8_LDA(At, 1, 1); PG8_STAGE(PG8_SB(1, 0), b3, voffB); PG8_STAGE(PG8_SB(1, 1), b3 + hstep, voffB); PG8_STAGE(PG8_SA(1, 0), a3, voffA);
;             PG8_WAIT_V(8); PG8_WAIT_L(0); PG8_BAR; PG8_MMA(1, 0, At, B0); PG8_MMA(1, 1, At, B1); PG8_BAR; PG8_SCHED;
	s_add_i32 s0, s62, s46
	v_lshl_add_u64 v[218:219], v[218:219], 0, s[8:9]
	s_mov_b32 m0, s0
	ds_read_b128 v[186:189], v155 offset:49152
	ds_read_b128 v[190:193], v155 offset:50176
	ds_read_b128 v[194:197], v155 offset:51200
	ds_read_b128 v[198:201], v155 offset:52224
	ds_read_b128 v[202:205], v155 offset:53248
	ds_read_b128 v[206:209], v155 offset:54272
	ds_read_b128 v[210:213], v155 offset:55296
	ds_read_b128 v[214:217], v155 offset:56320
	global_load_lds_dwordx4 v[218:219], off
	s_add_i32 m0, s0, 0x2000
	s_add_u32 s0, s42, 0x40080
	v_lshl_add_u64 v[218:219], v[220:221], 0, s[8:9]
	s_addc_u32 s1, s43, 0
	s_add_i32 s42, s63, s46
	global_load_lds_dwordx4 v[218:219], off
	v_lshl_add_u64 v[218:219], s[0:1], 0, v[132:133]
	s_mov_b32 m0, s42
	s_nop 0
	global_load_lds_dwordx4 v[218:219], off
	v_lshl_add_u64 v[218:219], s[0:1], 0, v[128:129]
	s_add_i32 m0, s42, 0x2000
	s_nop 0
	global_load_lds_dwordx4 v[218:219], off
	v_lshl_add_u64 v[218:219], v[222:223], 0, s[8:9]
	s_mov_b32 m0, s52
	s_nop 0
	global_load_lds_dwordx4 v[218:219], off
	v_lshl_add_u64 v[218:219], v[224:225], 0, s[8:9]
	s_mov_b32 m0, s53
	s_nop 0
	global_load_lds_dwordx4 v[218:219], off
	s_waitcnt vmcnt(8)
	s_waitcnt lgkmcnt(0)
	s_barrier
	s_setprio 1
	v_mfma_f32_16x16x32_bf16 v[60:63], v[146:149], v[186:189], v[60:63]
	v_mfma_f32_16x16x32_bf16 v[56:59], v[162:165], v[186:189], v[56:59]
	v_mfma_f32_16x16x32_bf16 v[44:47], v[146:149], v[194:197], v[44:47]
	v_mfma_f32_16x16x32_bf16 v[40:43], v[162:165], v[194:197], v[40:43]
	v_mfma_f32_16x16x32_bf16 v[28:31], v[146:149], v[202:205], v[28:31]
	v_mfma_f32_16x16x32_bf16 v[24:27], v[162:165], v[202:205], v[24:27]
	v_mfma_f32_16x16x32_bf16 v[12:15], v[146:149], v[210:213], v[12:15]
	v_mfma_f32_16x16x32_bf16 v[8:11], v[162:165], v[210:213], v[8:11]
	v_mfma_f32_16x16x32_bf16 v[60:63], v[158:161], v[190:193], v[60:63]
	v_mfma_f32_16x16x32_bf16 v[56:59], v[166:169], v[190:193], v[56:59]
	v_mfma_f32_16x16x32_bf16 v[44:47], v[158:161], v[198:201], v[44:47]
	v_mfma_f32_16x16x32_bf16 v[40:43], v[166:169], v[198:201], v[40:43]
	v_mfma_f32_16x16x32_bf16 v[28:31], v[158:161], v[206:209], v[28:31]
	v_mfma_f32_16x16x32_bf16 v[24:27], v[166:169], v[206:209], v[24:27]
	v_mfma_f32_16x16x32_bf16 v[12:15], v[158:161], v[214:217], v[12:15]
	v_mfma_f32_16x16x32_bf16 v[8:11], v[166:169], v[214:217], v[8:11]
	v_mfma_f32_16x16x32_bf16 v[52:55], v[170:173], v[186:189], v[52:55]
	v_mfma_f32_16x16x32_bf16 v[48:51], v[178:181], v[186:189], v[48:51]
	v_mfma_f32_16x16x32_bf16 v[36:39], v[170:173], v[194:197], v[36:39]
	v_mfma_f32_16x16x32_bf16 v[32:35], v[178:181], v[194:197], v[32:35]
	v_mfma_f32_16x16x32_bf16 v[20:23], v[170:173], v[202:205], v[20:23]
	v_mfma_f32_16x16x32_bf16 v[16:19], v[178:181], v[202:205], v[16:19]
	v_mfma_f32_16x16x32_bf16 v[4:7], v[170:173], v[210:213], v[4:7]
	v_mfma_f32_16x16x32_bf16 v[0:3], v[178:181], v[210:213], v[0:3]
	v_mfma_f32_16x16x32_bf16 v[52:55], v[174:177], v[190:193], v[52:55]
	v_mfma_f32_16x16x32_bf16 v[48:51], v[182:185], v[190:193], v[48:51]
	v_mfma_f32_16x16x32_bf16 v[36:39], v[174:177], v[198:201], v[36:39]
	v_mfma_f32_16x16x32_bf16 v[32:35], v[182:185], v[198:201], v[32:35]
	v_mfma_f32_16x16x32_bf16 v[20:23], v[174:177], v[206:209], v[20:23]
	v_mfma_f32_16x16x32_bf16 v[16:19], v[182:185], v[206:209], v[16:19]
	v_mfma_f32_16x16x32_bf16 v[4:7], v[174:177], v[214:217], v[4:7]
	v_mfma_f32_16x16x32_bf16 v[0:3], v[182:185], v[214:217], v[0:3]
	s_setprio 0
	s_barrier
	s_add_i32 s61, s61, 2
	s_add_u32 s40, s40, 0x100
	s_addc_u32 s41, s41, 0
	s_add_u32 s59, s59, 0x100
	s_addc_u32 s60, s60, 0
	s_cmp_gt_u32 s61, 13
	s_cbranch_scc0 .LBB0_391
	s_and_b64 vcc, exec, s[10:11]
	s_cbranch_vccz .LBB0_394
	s_barrier

; #define PG8_STAGE(bufoff, gbase, voff) do { _Pragma("unroll") for (int _i = 0; _i < 2; ++_i) { unsigned vo_ = (voff)[_i]; if constexpr (FP8) asm volatile("" : "+v"(vo_)); \
;         __builtin_amdgcn_global_load_lds((const unsigned*)((const char*)(gbase) + vo_), (PG8_LAS unsigned*)(lds + (bufoff) + ldsw + _i * 8192), 16, 0, 0); } } while (0)
; #define PG8_LDA(dst, b, h) do { _Pragma("unroll") for (int m = 0; m < 4; ++m) _Pragma("unroll") for (int k = 0; k < 2; ++k) dst[m][k] = *(const PG8_LAS bf16x8*)(lds + PG8_SA(b, h) + aoff + m * 2048 + k * 1024); } while (0)
; #define PG8_LDB(dst, b, h) do { _Pragma("unroll") for (int n = 0; n < 2; ++n) _Pragma("unroll") for (int k = 0; k < 2; ++k) dst[n][k] = *(const PG8_LAS bf16x8*)(lds + PG8_SB(b, h) + boff + n * 2048 + k * 1024); } while (0)
; #define PG8_WAIT_V(n) asm volatile("s_waitcnt vmcnt(" #n ")" ::: "memory")
; #define PG8_WAIT_L(n) asm volatile("s_waitcnt lgkmcnt(" #n ")" ::: "memory")
; #define PG8_BAR __builtin_amdgcn_s_barrier()
; #define PG8_SCHED __builtin_amdgcn_sched_barrier(0)
; template <class Epi, class Sched, bool ALIGN_EPI = false, bool SP2 = false, bool FP8 = false>
; __device__ __forceinline__ void gemm_phase(PG8_LAS unsigned char* lds, const Gemm g, const Sched& S, const Epi& E) {
;     ...
;             const bool last = (t == nt - 2);
;             const char* a1 = cA + (size_t)(t + 1) * kstep;
;             const char* a2 = last ? nA : cA + (size_t)(t + 2) * kstep; const char* b2 = last ? nB : cB + (size_t)(t + 2) * kstep;
;             const char* a3 = a2 + kstep; const char* b3 = b2 + kstep;
;             if (last && has_next) S.a_ready(nxt);
;             if constexpr (SP2) {
;             PG8_LDB(B0, 0, 0); PG8_LDB(B1, 0, 1); PG8_SCHED; PG8_LDA(At, 0, 0); PG8_STAGE(PG8_SA(1, 1), a1 + hstep, voffA);
;             PG8_WAIT_V(8); PG8_WAIT_L(0); PG8_BAR; PG8_MMA(0, 0, At, B0); PG8_MMA(0, 1, At, B1); PG8_BAR; PG8_SCHED;
;             PG8_LDA(At, 0, 1); PG8_STAGE(PG8_SB(0, 0), b2, voffB); PG8_STAGE(PG8_SB(0, 1), b2 + hstep, voffB); PG8_STAGE(PG8_SA(0, 0), a2, voffA);
;             PG8_WAIT_V(8); PG8_WAIT_L(0); PG8_BAR; PG8_MMA(1, 0, At, B0); PG8_MMA(1, 1, At, B1); PG8_BAR; PG8_SCHED;
.Lmy_nobar_P6:
.LBB0_427:
	ds_read_b128 v[128:131], v201
	ds_read_b128 v[132:135], v201 offset:1024
	ds_read_b128 v[136:139], v201 offset:2048
	ds_read_b128 v[140:143], v201 offset:3072
	ds_read_b128 v[144:147], v202
	ds_read_b128 v[148:151], v202 offset:1024
	ds_read_b128 v[170:173], v202 offset:2048
	ds_read_b128 v[174:177], v202 offset:3072
	s_add_u32 s42, s40, 0xfff00080
	s_addc_u32 s43, s41, -1
	s_cmp_eq_u32 s63, 60
	s_cselect_b32 s45, s31, s43
	s_cselect_b32 s44, s39, s42
	s_cselect_b32 s43, s23, s62
	s_cselect_b32 s42, s60, s61
	v_lshl_add_u64 v[218:219], s[40:41], 0, v[162:163]
	s_add_i32 m0, s47, 0xc000
	ds_read_b128 v[178:181], v203
	ds_read_b128 v[182:185], v203 offset:1024
	ds_read_b128 v[186:189], v203 offset:2048
	ds_read_b128 v[190:193], v203 offset:3072
	ds_read_b128 v[194:197], v203 offset:4096
	ds_read_b128 v[206:209], v203 offset:5120
	ds_read_b128 v[210:213], v203 offset:6144
	ds_read_b128 v[214:217], v203 offset:7168
	global_load_lds_dwordx4 v[218:219], off
	v_lshl_add_u64 v[218:219], s[40:41], 0, v[164:165]
	s_add_i32 m0, s47, 0xe000
	s_nop 0
	global_load_lds_dwordx4 v[218:219], off
	s_waitcnt vmcnt(8)
	s_waitcnt lgkmcnt(0)
	s_barrier
	s_setprio 1
	v_mfma_f32_16x16x32_bf16 v[124:127], v[128:131], v[178:181], v[124:127]
	v_mfma_f32_16x16x32_bf16 v[120:123], v[136:139], v[178:181], v[120:123]
	v_mfma_f32_16x16x32_bf16 v[108:111], v[128:131], v[186:189], v[108:111]
	v_mfma_f32_16x16x32_bf16 v[104:107], v[136:139], v[186:189], v[104:107]
	v_mfma_f32_16x16x32_bf16 v[92:95], v[128:131], v[194:197], v[92:95]
	v_mfma_f32_16x16x32_bf16 v[88:91], v[136:139], v[194:197], v[88:91]
	v_mfma_f32_16x16x32_bf16 v[76:79], v[128:131], v[210:213], v[76:79]
	v_mfma_f32_16x16x32_bf16 v[72:75], v[136:139], v[210:213], v[72:75]
	v_mfma_f32_16x16x32_bf16 v[124:127], v[132:135], v[182:185], v[124:127]
	v_mfma_f32_16x16x32_bf16 v[120:123], v[140:143], v[182:185], v[120:123]
	v_mfma_f32_16x16x32_bf16 v[108:111], v[132:135], v[190:193], v[108:111]
	v_mfma_f32_16x16x32_bf16 v[104:107], v[140:143], v[190:193], v[104:107]
	v_mfma_f32_16x16x32_bf16 v[92:95], v[132:135], v[206:209], v[92:95]
	v_mfma_f32_16x16x32_bf16 v[88:91], v[140:143], v[206:209], v[88:91]
	v_mfma_f32_16x16x32_bf16 v[76:79], v[132:135], v[214:217], v[76:79]
	v_mfma_f32_16x16x32_bf16 v[72:75], v[140:143], v[214:217], v[72:75]
	v_mfma_f32_16x16x32_bf16 v[116:119], v[144:147], v[178:181], v[116:119]
	v_mfma_f32_16x16x32_bf16 v[112:115], v[170:173], v[178:181], v[112:115]
	v_mfma_f32_16x16x32_bf16 v[100:103], v[144:147], v[186:189], v[100:103]
	v_mfma_f32_16x16x32_bf16 v[96:99], v[170:173], v[186:189], v[96:99]
	v_mfma_f32_16x16x32_bf16 v[84:87], v[144:147], v[194:197], v[84:87]
	v_mfma_f32_16x16x32_bf16 v[80:83], v[170:173], v[194:197], v[80:83]
	v_mfma_f32_16x16x32_bf16 v[68:71], v[144:147], v[210:213], v[68:71]
	v_mfma_f32_16x16x32_bf16 v[64:67], v[170:173], v[210:213], v[64:67]
	v_mfma_f32_16x16x32_bf16 v[116:119], v[148:151], v[182:185], v[116:119]
	v_mfma_f32_16x16x32_bf16 v[112:115], v[174:177], v[182:185], v[112:115]
	v_mfma_f32_16x16x32_bf16 v[100:103], v[148:151], v[190:193], v[100:103]
	v_mfma_f32_16x16x32_bf16 v[96:99], v[174:177], v[190:193], v[96:99]
	v_mfma_f32_16x16x32_bf16 v[84:87], v[148:151], v[206:209], v[84:87]
	v_mfma_f32_16x16x32_bf16 v[80:83], v[174:177], v[206:209], v[80:83]
	v_mfma_f32_16x16x32_bf16 v[68:71], v[148:151], v[214:217], v[68:71]
	v_mfma_f32_16x16x32_bf16 v[64:67], v[174:177], v[214:217], v[64:67]
	s_setprio 0
	s_barrier
	s_add_i32 s64, s57, s46
	v_lshl_add_u64 v[218:219], s[42:43], 0, v[154:155]
	s_mov_b32 m0, s64
	ds_read_b128 v[178:181], v203 offset:16384
	ds_read_b128 v[182:185], v203 offset:17408
	ds_read_b128 v[186:189], v203 offset:18432
	ds_read_b128 v[190:193], v203 offset:19456
	ds_read_b128 v[194:197], v203 offset:20480
	ds_read_b128 v[206:209], v203 offset:21504
	ds_read_b128 v[210:213], v203 offset:22528
	ds_read_b128 v[214:217], v203 offset:23552
	global_load_lds_dwordx4 v[218:219], off
	s_add_i32 m0, s64, 0x2000
	s_add_u32 s64, s42, 0x100000
	v_lshl_add_u64 v[220:221], s[42:43], 0, v[158:159]
	s_addc_u32 s65, s43, 0
	s_add_i32 s66, s58, s46
	global_load_lds_dwordx4 v[220:221], off
	v_lshl_add_u64 v[222:223], s[64:65], 0, v[154:155]
	s_mov_b32 m0, s66
	v_lshl_add_u64 v[224:225], s[44:45], 0, v[156:157]
	global_load_lds_dwordx4 v[222:223], off
	v_lshl_add_u64 v[222:223], s[64:65], 0, v[158:159]
	s_add_i32 m0, s66, 0x2000
	s_nop 0
	global_load_lds_dwordx4 v[222:223], off
	v_lshl_add_u64 v[222:223], s[44:45], 0, v[152:153]
	s_mov_b32 m0, s47
	s_nop 0
	global_load_lds_dwordx4 v[222:223], off
	s_mov_b32 m0, s48
	s_nop 0
	global_load_lds_dwordx4 v[224:225], off
	s_waitcnt vmcnt(8)
	s_waitcnt lgkmcnt(0)
	s_barrier
; #define PG8_STAGE(bufoff, gbase, voff) do { _Pragma("unroll") for (int _i = 0; _i < 2; ++_i) { unsigned vo_ = (voff)[_i]; if constexpr (FP8) asm volatile("" : "+v"(vo_)); \
;         __builtin_amdgcn_global_load_lds((const unsigned*)((const char*)(gbase) + vo_), (PG8_LAS unsigned*)(lds + (bufoff) + ldsw + _i * 8192), 16, 0, 0); } } while (0)
; #define PG8_LDA(dst, b, h) do { _Pragma("unroll") for (int m = 0; m < 4; ++m) _Pragma("unroll") for (int k = 0; k < 2; ++k) dst[m][k] = *(const PG8_LAS bf16x8*)(lds + PG8_SA(b, h) + aoff + m * 2048 + k * 1024); } while (0)
; #define PG8_LDB(dst, b, h) do { _Pragma("unroll") for (int n = 0; n < 2; ++n) _Pragma("unroll") for (int k = 0; k < 2; ++k) dst[n][k] = *(const PG8_LAS bf16x8*)(lds + PG8_SB(b, h) + boff + n * 2048 + k * 1024); } while (0)
; #define PG8_WAIT_V(n) asm volatile("s_waitcnt vmcnt(" #n ")" ::: "memory")
; #define PG8_WAIT_L(n) asm volatile("s_waitcnt lgkmcnt(" #n ")" ::: "memory")
; #define PG8_BAR __builtin_amdgcn_s_barrier()
; #define PG8_SCHED __builtin_amdgcn_sched_barrier(0)
; template <class Epi, class Sched, bool ALIGN_EPI = false, bool SP2 = false, bool FP8 = false>
; __device__ __forceinline__ void gemm_phase(PG8_LAS unsigned char* lds, const Gemm g, const Sched& S, const Epi& E) {
;     ...
;             PG8_WAIT_V(8); PG8_WAIT_L(0); PG8_BAR; PG8_MMA(1, 0, At, B0); PG8_MMA(1, 1, At, B1); PG8_BAR; PG8_SCHED;
;             PG8_LDB(B0, 1, 0); PG8_LDB(B1, 1, 1); PG8_SCHED; PG8_LDA(At, 1, 0); PG8_STAGE(PG8_SA(0, 1), a2 + hstep, voffA);
;             PG8_WAIT_V(8); PG8_WAIT_L(0); PG8_BAR; PG8_MMA(0, 0, At, B0); PG8_MMA(0, 1, At, B1); PG8_BAR; PG8_SCHED;
	s_setprio 1
	v_mfma_f32_16x16x32_bf16 v[60:63], v[128:131], v[178:181], v[60:63]
	v_mfma_f32_16x16x32_bf16 v[56:59], v[136:139], v[178:181], v[56:59]
	v_mfma_f32_16x16x32_bf16 v[44:47], v[128:131], v[186:189], v[44:47]
	v_mfma_f32_16x16x32_bf16 v[40:43], v[136:139], v[186:189], v[40:43]
	v_mfma_f32_16x16x32_bf16 v[28:31], v[128:131], v[194:197], v[28:31]
	v_mfma_f32_16x16x32_bf16 v[24:27], v[136:139], v[194:197], v[24:27]
	v_mfma_f32_16x16x32_bf16 v[12:15], v[128:131], v[210:213], v[12:15]
	v_mfma_f32_16x16x32_bf16 v[8:11], v[136:139], v[210:213], v[8:11]
	v_mfma_f32_16x16x32_bf16 v[60:63], v[132:135], v[182:185], v[60:63]
	v_mfma_f32_16x16x32_bf16 v[56:59], v[140:143], v[182:185], v[56:59]
	v_mfma_f32_16x16x32_bf16 v[44:47], v[132:135], v[190:193], v[44:47]
	v_mfma_f32_16x16x32_bf16 v[40:43], v[140:143], v[190:193], v[40:43]
	v_mfma_f32_16x16x32_bf16 v[28:31], v[132:135], v[206:209], v[28:31]
	v_mfma_f32_16x16x32_bf16 v[24:27], v[140:143], v[206:209], v[24:27]
	v_mfma_f32_16x16x32_bf16 v[12:15], v[132:135], v[214:217], v[12:15]
	v_mfma_f32_16x16x32_bf16 v[8:11], v[140:143], v[214:217], v[8:11]
	v_mfma_f32_16x16x32_bf16 v[52:55], v[144:147], v[178:181], v[52:55]
	v_mfma_f32_16x16x32_bf16 v[48:51], v[170:173], v[178:181], v[48:51]
	v_mfma_f32_16x16x32_bf16 v[36:39], v[144:147], v[186:189], v[36:39]
	v_mfma_f32_16x16x32_bf16 v[32:35], v[170:173], v[186:189], v[32:35]
	v_mfma_f32_16x16x32_bf16 v[20:23], v[144:147], v[194:197], v[20:23]
	v_mfma_f32_16x16x32_bf16 v[16:19], v[170:173], v[194:197], v[16:19]
	v_mfma_f32_16x16x32_bf16 v[4:7], v[144:147], v[210:213], v[4:7]
	v_mfma_f32_16x16x32_bf16 v[0:3], v[170:173], v[210:213], v[0:3]
	v_mfma_f32_16x16x32_bf16 v[52:55], v[148:151], v[182:185], v[52:55]
	v_mfma_f32_16x16x32_bf16 v[48:51], v[174:177], v[182:185], v[48:51]
	v_mfma_f32_16x16x32_bf16 v[36:39], v[148:151], v[190:193], v[36:39]
	v_mfma_f32_16x16x32_bf16 v[32:35], v[174:177], v[190:193], v[32:35]
	v_mfma_f32_16x16x32_bf16 v[20:23], v[148:151], v[206:209], v[20:23]
	v_mfma_f32_16x16x32_bf16 v[16:19], v[174:177], v[206:209], v[16:19]
	v_mfma_f32_16x16x32_bf16 v[4:7], v[148:151], v[214:217], v[4:7]
	v_mfma_f32_16x16x32_bf16 v[0:3], v[174:177], v[214:217], v[0:3]
	s_setprio 0
	s_barrier
	s_add_i32 s64, 0, 0x18000
	s_add_i32 s65, 0, 0x1c000
	v_add_u32_e32 v140, s64, v199
	v_add_u32_e32 v174, s65, v199
	ds_read_b128 v[128:131], v140
	ds_read_b128 v[132:135], v140 offset:1024
	ds_read_b128 v[136:139], v140 offset:2048
	ds_read_b128 v[140:143], v140 offset:3072
	ds_read_b128 v[144:147], v174
	ds_read_b128 v[148:151], v174 offset:1024
	ds_read_b128 v[170:173], v174 offset:2048
	ds_read_b128 v[174:177], v174 offset:3072
	s_add_u32 s44, s44, 0x100000
	s_addc_u32 s45, s45, 0
	s_mov_b32 m0, s49
	v_lshl_add_u64 v[226:227], s[44:45], 0, v[152:153]
	ds_read_b128 v[178:181], v203 offset:32768
	ds_read_b128 v[182:185], v203 offset:33792
	ds_read_b128 v[186:189], v203 offset:34816
	ds_read_b128 v[190:193], v203 offset:35840
	ds_read_b128 v[194:197], v203 offset:36864
	ds_read_b128 v[206:209], v203 offset:37888
	ds_read_b128 v[210:213], v203 offset:38912
	ds_read_b128 v[214:217], v203 offset:39936
	global_load_lds_dwordx4 v[226:227], off
	v_lshl_add_u64 v[226:227], s[44:45], 0, v[156:157]
	s_mov_b32 m0, s50
	s_nop 0
	global_load_lds_dwordx4 v[226:227], off
	s_waitcnt vmcnt(8)
	s_waitcnt lgkmcnt(0)
	s_barrier
	s_setprio 1
	v_mfma_f32_16x16x32_bf16 v[124:127], v[128:131], v[178:181], v[124:127]
	v_mfma_f32_16x16x32_bf16 v[120:123], v[136:139], v[178:181], v[120:123]
	v_mfma_f32_16x16x32_bf16 v[108:111], v[128:131], v[186:189], v[108:111]
	v_mfma_f32_16x16x32_bf16 v[104:107], v[136:139], v[186:189], v[104:107]
	v_mfma_f32_16x16x32_bf16 v[92:95], v[128:131], v[194:197], v[92:95]
	v_mfma_f32_16x16x32_bf16 v[88:91], v[136:139], v[194:197], v[88:91]
	v_mfma_f32_16x16x32_bf16 v[76:79], v[128:131], v[210:213], v[76:79]
	v_mfma_f32_16x16x32_bf16 v[72:75], v[136:139], v[210:213], v[72:75]
	v_mfma_f32_16x16x32_bf16 v[124:127], v[132:135], v[182:185], v[124:127]
	v_mfma_f32_16x16x32_bf16 v[120:123], v[140:143], v[182:185], v[120:123]
	v_mfma_f32_16x16x32_bf16 v[108:111], v[132:135], v[190:193], v[108:111]
	v_mfma_f32_16x16x32_bf16 v[104:107], v[140:143], v[190:193], v[104:107]
	v_mfma_f32_16x16x32_bf16 v[92:95], v[132:135], v[206:209], v[92:95]
	v_mfma_f32_16x16x32_bf16 v[88:91], v[140:143], v[206:209], v[88:91]
	v_mfma_f32_16x16x32_bf16 v[76:79], v[132:135], v[214:217], v[76:79]
	v_mfma_f32_16x16x32_bf16 v[72:75], v[140:143], v[214:217], v[72:75]
	v_mfma_f32_16x16x32_bf16 v[116:119], v[144:147], v[178:181], v[116:119]
	v_mfma_f32_16x16x32_bf16 v[112:115], v[170:173], v[178:181], v[112:115]
	v_mfma_f32_16x16x32_bf16 v[100:103], v[144:147], v[186:189], v[100:103]
	v_mfma_f32_16x16x32_bf16 v[96:99], v[170:173], v[186:189], v[96:99]
	v_mfma_f32_16x16x32_bf16 v[84:87], v[144:147], v[194:197], v[84:87]
	v_mfma_f32_16x16x32_bf16 v[80:83], v[170:173], v[194:197], v[80:83]
	v_mfma_f32_16x16x32_bf16 v[68:71], v[144:147], v[210:213], v[68:71]
	v_mfma_f32_16x16x32_bf16 v[64:67], v[170:173], v[210:213], v[64:67]
	v_mfma_f32_16x16x32_bf16 v[116:119], v[148:151], v[182:185], v[116:119]
	v_mfma_f32_16x16x32_bf16 v[112:115], v[174:177], v[182:185], v[112:115]
	v_mfma_f32_16x16x32_bf16 v[100:103], v[148:151], v[190:193], v[100:103]
	v_mfma_f32_16x16x32_bf16 v[96:99], v[174:177], v[190:193], v[96:99]
	v_mfma_f32_16x16x32_bf16 v[84:87], v[148:151], v[206:209], v[84:87]
	v_mfma_f32_16x16x32_bf16 v[80:83], v[174:177], v[206:209], v[80:83]
	v_mfma_f32_16x16x32_bf16 v[68:71], v[148:151], v[214:217], v[68:71]
	v_mfma_f32_16x16x32_bf16 v[64:67], v[174:177], v[214:217], v[64:67]
	s_setprio 0
	s_barrier
; #define PG8_STAGE(bufoff, gbase, voff) do { _Pragma("unroll") for (int _i = 0; _i < 2; ++_i) { unsigned vo_ = (voff)[_i]; if constexpr (FP8) asm volatile("" : "+v"(vo_)); \
;         __builtin_amdgcn_global_load_lds((const unsigned*)((const char*)(gbase) + vo_), (PG8_LAS unsigned*)(lds + (bufoff) + ldsw + _i * 8192), 16, 0, 0); } } while (0)
; #define PG8_LDA(dst, b, h) do { _Pragma("unroll") for (int m = 0; m < 4; ++m) _Pragma("unroll") for (int k = 0; k < 2; ++k) dst[m][k] = *(const PG8_LAS bf16x8*)(lds + PG8_SA(b, h) + aoff + m * 2048 + k * 1024); } while (0)
; #define PG8_WAIT_V(n) asm volatile("s_waitcnt vmcnt(" #n ")" ::: "memory")
; #define PG8_WAIT_L(n) asm volatile("s_waitcnt lgkmcnt(" #n ")" ::: "memory")
; #define PG8_BAR __builtin_amdgcn_s_barrier()
; #define PG8_SCHED __builtin_amdgcn_sched_barrier(0)
; template <class Epi, class Sched, bool ALIGN_EPI = false, bool SP2 = false, bool FP8 = false>
; __device__ __forceinline__ void gemm_phase(PG8_LAS unsigned char* lds, const Gemm g, const Sched& S, const Epi& E) {
;     ...
;             PG8_LDA(At, 1, 1); PG8_STAGE(PG8_SB(1, 0), b3, voffB); PG8_STAGE(PG8_SB(1, 1), b3 + hstep, voffB); PG8_STAGE(PG8_SA(1, 0), a3, voffA);
;             PG8_WAIT_V(8); PG8_WAIT_L(0); PG8_BAR; PG8_MMA(1, 0, At, B0); PG8_MMA(1, 1, At, B1); PG8_BAR; PG8_SCHED;
	s_add_i32 s44, s64, s46
	v_lshl_add_u64 v[218:219], v[218:219], 0, s[12:13]
	s_mov_b32 m0, s44
	ds_read_b128 v[178:181], v203 offset:49152
	ds_read_b128 v[182:185], v203 offset:50176
	ds_read_b128 v[186:189], v203 offset:51200
	ds_read_b128 v[190:193], v203 offset:52224
	ds_read_b128 v[194:197], v203 offset:53248
	ds_read_b128 v[206:209], v203 offset:54272
	ds_read_b128 v[210:213], v203 offset:55296
	ds_read_b128 v[214:217], v203 offset:56320
	global_load_lds_dwordx4 v[218:219], off
	s_add_i32 m0, s44, 0x2000
	s_add_u32 s42, s42, 0x100080
	v_lshl_add_u64 v[218:219], v[220:221], 0, s[12:13]
	s_addc_u32 s43, s43, 0
	s_add_i32 s44, s65, s46
	global_load_lds_dwordx4 v[218:219], off
	v_lshl_add_u64 v[218:219], s[42:43], 0, v[154:155]
	s_mov_b32 m0, s44
	s_nop 0
	global_load_lds_dwordx4 v[218:219], off
	v_lshl_add_u64 v[218:219], s[42:43], 0, v[158:159]
	s_add_i32 m0, s44, 0x2000
	s_nop 0
	global_load_lds_dwordx4 v[218:219], off
	v_lshl_add_u64 v[218:219], v[222:223], 0, s[12:13]
	s_mov_b32 m0, s54
	s_nop 0
	global_load_lds_dwordx4 v[218:219], off
	v_lshl_add_u64 v[218:219], v[224:225], 0, s[12:13]
	s_mov_b32 m0, s55
	s_nop 0
	global_load_lds_dwordx4 v[218:219], off
	s_waitcnt vmcnt(8)
	s_waitcnt lgkmcnt(0)
	s_barrier
	s_setprio 1
	v_mfma_f32_16x16x32_bf16 v[60:63], v[128:131], v[178:181], v[60:63]
	v_mfma_f32_16x16x32_bf16 v[56:59], v[136:139], v[178:181], v[56:59]
	v_mfma_f32_16x16x32_bf16 v[44:47], v[128:131], v[186:189], v[44:47]
	v_mfma_f32_16x16x32_bf16 v[40:43], v[136:139], v[186:189], v[40:43]
	v_mfma_f32_16x16x32_bf16 v[28:31], v[128:131], v[194:197], v[28:31]
	v_mfma_f32_16x16x32_bf16 v[24:27], v[136:139], v[194:197], v[24:27]
	v_mfma_f32_16x16x32_bf16 v[12:15], v[128:131], v[210:213], v[12:15]
	v_mfma_f32_16x16x32_bf16 v[8:11], v[136:139], v[210:213], v[8:11]
	v_mfma_f32_16x16x32_bf16 v[60:63], v[132:135], v[182:185], v[60:63]
	v_mfma_f32_16x16x32_bf16 v[56:59], v[140:143], v[182:185], v[56:59]
	v_mfma_f32_16x16x32_bf16 v[44:47], v[132:135], v[190:193], v[44:47]
	v_mfma_f32_16x16x32_bf16 v[40:43], v[140:143], v[190:193], v[40:43]
	v_mfma_f32_16x16x32_bf16 v[28:31], v[132:135], v[206:209], v[28:31]
	v_mfma_f32_16x16x32_bf16 v[24:27], v[140:143], v[206:209], v[24:27]
	v_mfma_f32_16x16x32_bf16 v[12:15], v[132:135], v[214:217], v[12:15]
	v_mfma_f32_16x16x32_bf16 v[8:11], v[140:143], v[214:217], v[8:11]
	v_mfma_f32_16x16x32_bf16 v[52:55], v[144:147], v[178:181], v[52:55]
	v_mfma_f32_16x16x32_bf16 v[48:51], v[170:173], v[178:181], v[48:51]
	v_mfma_f32_16x16x32_bf16 v[36:39], v[144:147], v[186:189], v[36:39]
	v_mfma_f32_16x16x32_bf16 v[32:35], v[170:173], v[186:189], v[32:35]
	v_mfma_f32_16x16x32_bf16 v[20:23], v[144:147], v[194:197], v[20:23]
	v_mfma_f32_16x16x32_bf16 v[16:19], v[170:173], v[194:197], v[16:19]
	v_mfma_f32_16x16x32_bf16 v[4:7], v[144:147], v[210:213], v[4:7]
	v_mfma_f32_16x16x32_bf16 v[0:3], v[170:173], v[210:213], v[0:3]
	v_mfma_f32_16x16x32_bf16 v[52:55], v[148:151], v[182:185], v[52:55]
	v_mfma_f32_16x16x32_bf16 v[48:51], v[174:177], v[182:185], v[48:51]
	v_mfma_f32_16x16x32_bf16 v[36:39], v[148:151], v[190:193], v[36:39]
	v_mfma_f32_16x16x32_bf16 v[32:35], v[174:177], v[190:193], v[32:35]
	v_mfma_f32_16x16x32_bf16 v[20:23], v[148:151], v[206:209], v[20:23]
	v_mfma_f32_16x16x32_bf16 v[16:19], v[174:177], v[206:209], v[16:19]
	v_mfma_f32_16x16x32_bf16 v[4:7], v[148:151], v[214:217], v[4:7]
	v_mfma_f32_16x16x32_bf16 v[0:3], v[174:177], v[214:217], v[0:3]
	s_setprio 0
	s_barrier
	s_add_i32 s63, s63, 2
	s_add_u32 s40, s40, 0x100
	s_addc_u32 s41, s41, 0
	s_add_u32 s61, s61, 0x100
	s_addc_u32 s62, s62, 0
	s_cmp_gt_u32 s63, 61
	s_cbranch_scc0 .LBB0_427
	s_and_b64 vcc, exec, s[14:15]
	s_cbranch_vccz .LBB0_430
